# P3 v10: v9 + L2-warming touch loads (one dword per 128B line, split over the 8 v-slice workgroups) issued by the o-waves 5-6 steps ahead
# speedup vs baseline: 1.0010x; 1.0010x over previous
; #define LAS __attribute__((address_space(3)))
; __device__ __forceinline__ void gla_scan_item(const Ctx& C, int item, LAS unsigned char* lds, int tid) {
;     const int jx = item >> 3, bh = (item & 7) * 4 + (jx >> 3), sl = jx & 7, b = bh >> 2, h = bh & 3;
;     LAS bf16* Aq = (LAS bf16*)lds;
;     LAS bf16* Bc = (LAS bf16*)(lds + 25600);
;     LAS bf16* Kt = (LAS bf16*)(lds + 38400);
;     const int wave = tid >> 6, lane = tid & 63, l15 = lane & 15, quad = lane >> 4;
;     f32x4 S[2] = {(f32x4){0.f, 0.f, 0.f, 0.f}, (f32x4){0.f, 0.f, 0.f, 0.f}};
;     *(LAS u32x4*)(Bc + (tid >> 4) * 200 + (tid & 15) * 8) = (u32x4){0u, 0u, 0u, 0u};
;     u32x4 rq0A, rq1A, rsA, rk0A, rk1A, rvA = (u32x4){0u, 0u, 0u, 0u}; f32x4 rdA;
;     u32x4 rq0B, rq1B, rsB, rk0B, rk1B, rvB = (u32x4){0u, 0u, 0u, 0u}; f32x4 rdB;
.LBB0_428:
	s_cmp_lt_i32 s96, 4
	s_cselect_b64 s[4:5], -1, 0
	s_add_u32 s6, s94, 0xb300000
	s_addc_u32 s7, s95, 0
	s_and_b64 s[0:1], s[4:5], s[0:1]
	s_andn2_b64 vcc, exec, s[0:1]
	s_cbranch_vccnz .LBB0_496
	s_cmpk_gt_i32 s2, 0xff
	s_cbranch_scc1 .LBB0_496
	v_readfirstlane_b32 s32, v163
	v_and_b32_e32 v208, 63, v162
	v_and_b32_e32 v207, 15, v162
	v_bfe_u32 v206, v162, 4, 2
	v_and_b32_e32 v196, 3, v163
	v_lshlrev_b32_e32 v196, 1, v196
	v_lshrrev_b32_e32 v205, 4, v208
	v_lshl_add_u32 v205, v196, 3, v205
	v_and_b32_e32 v204, 15, v205
	v_xor_b32_e32 v204, v204, v207
	v_lshlrev_b32_e32 v195, 10, v205
	v_lshl_add_u32 v195, v204, 4, v195
	v_lshrrev_b32_e32 v205, 4, v208
	v_lshl_add_u32 v205, v196, 3, v205
	v_add_u32_e32 v205, 4, v205
	v_and_b32_e32 v204, 15, v205
	v_xor_b32_e32 v204, v204, v207
	v_lshlrev_b32_e32 v194, 10, v205
	v_lshl_add_u32 v194, v204, 4, v194
	v_lshrrev_b32_e32 v205, 3, v208
	v_lshl_add_u32 v205, v196, 3, v205
	v_bfe_u32 v204, v205, 1, 3
	v_and_b32_e32 v203, 7, v208
	v_xor_b32_e32 v204, v204, v203
	v_lshlrev_b32_e32 v191, 7, v205
	v_lshl_add_u32 v191, v204, 4, v191
	v_lshrrev_b32_e32 v205, 3, v208
	v_lshl_add_u32 v205, v196, 4, v205
	v_bfe_u32 v204, v205, 1, 3
	v_and_b32_e32 v203, 7, v208
	v_xor_b32_e32 v204, v204, v203
	v_lshlrev_b32_e32 v189, 7, v205
	v_lshl_add_u32 v189, v204, 4, v189
	v_lshrrev_b32_e32 v205, 3, v208
	v_lshl_add_u32 v205, v196, 4, v205
	v_add_u32_e32 v205, 8, v205
	v_bfe_u32 v204, v205, 1, 3
	v_and_b32_e32 v203, 7, v208
	v_xor_b32_e32 v204, v204, v203
	v_lshlrev_b32_e32 v188, 7, v205
	v_lshl_add_u32 v188, v204, 4, v188
	v_add_u32_e32 v196, 1, v196
	v_lshrrev_b32_e32 v205, 4, v208
	v_lshl_add_u32 v205, v196, 3, v205
	v_and_b32_e32 v204, 15, v205
	v_xor_b32_e32 v204, v204, v207
	v_lshlrev_b32_e32 v193, 10, v205
	v_lshl_add_u32 v193, v204, 4, v193
	v_lshrrev_b32_e32 v205, 4, v208
	v_lshl_add_u32 v205, v196, 3, v205
	v_add_u32_e32 v205, 4, v205
	v_and_b32_e32 v204, 15, v205
	v_xor_b32_e32 v204, v204, v207
	v_lshlrev_b32_e32 v192, 10, v205
	v_lshl_add_u32 v192, v204, 4, v192
	v_lshrrev_b32_e32 v205, 3, v208
	v_lshl_add_u32 v205, v196, 3, v205
	v_bfe_u32 v204, v205, 1, 3
	v_and_b32_e32 v203, 7, v208
	v_xor_b32_e32 v204, v204, v203
	v_lshlrev_b32_e32 v190, 7, v205
	v_lshl_add_u32 v190, v204, 4, v190
	v_lshrrev_b32_e32 v205, 3, v208
	v_lshl_add_u32 v205, v196, 4, v205
	v_bfe_u32 v204, v205, 1, 3
	v_and_b32_e32 v203, 7, v208
	v_xor_b32_e32 v204, v204, v203
	v_lshlrev_b32_e32 v187, 7, v205
	v_lshl_add_u32 v187, v204, 4, v187
	v_lshrrev_b32_e32 v205, 3, v208
	v_lshl_add_u32 v205, v196, 4, v205
	v_add_u32_e32 v205, 8, v205
	v_bfe_u32 v204, v205, 1, 3
	v_and_b32_e32 v203, 7, v208
	v_xor_b32_e32 v204, v204, v203
	v_lshlrev_b32_e32 v186, 7, v205
	v_lshl_add_u32 v186, v204, 4, v186
	s_and_b32 s4, s32, 3
	s_lshl_b32 s46, s4, 12
	s_lshl_b32 s47, s4, 11
	s_add_i32 s47, s47, 0x4000
	s_add_i32 s48, s46, 0x6000
	v_and_b32_e32 v205, 1, v163
	v_lshl_add_u32 v205, v205, 5, v207
	v_or_b32_e32 v204, 0, v206
	v_and_b32_e32 v203, 15, v205
	v_xor_b32_e32 v204, v204, v203
	v_lshlrev_b32_e32 v246, 8, v205
	v_lshl_add_u32 v246, v204, 4, v246
	v_or_b32_e32 v204, 4, v206
	v_and_b32_e32 v203, 15, v205
	v_xor_b32_e32 v204, v204, v203
	v_lshlrev_b32_e32 v245, 8, v205
	v_lshl_add_u32 v245, v204, 4, v245
	v_or_b32_e32 v204, 8, v206
	v_and_b32_e32 v203, 15, v205
	v_xor_b32_e32 v204, v204, v203
	v_lshlrev_b32_e32 v244, 8, v205
	v_lshl_add_u32 v244, v204, 4, v244
	v_or_b32_e32 v204, 12, v206
	v_and_b32_e32 v203, 15, v205
	v_xor_b32_e32 v204, v204, v203
	v_lshlrev_b32_e32 v243, 8, v205
	v_lshl_add_u32 v243, v204, 4, v243
	v_or_b32_e32 v204, 0, v206
	v_bfe_u32 v203, v205, 1, 3
	v_xor_b32_e32 v204, v204, v203
	v_lshlrev_b32_e32 v238, 7, v205
	v_lshl_add_u32 v238, v204, 4, v238
	v_add_u32_e32 v238, 0x4000, v238
	v_or_b32_e32 v204, 4, v206
	v_bfe_u32 v203, v205, 1, 3
	v_xor_b32_e32 v204, v204, v203
	v_lshlrev_b32_e32 v235, 7, v205
	v_lshl_add_u32 v235, v204, 4, v235
	v_add_u32_e32 v235, 0x4000, v235
	v_lshlrev_b32_e32 v253, 11, v205
	v_lshl_add_u32 v253, v206, 3, v253
	v_add_u32_e32 v252, 0x8000, v253
	v_or_b32_e32 v204, 0, v206
	v_and_b32_e32 v203, 15, v207
	v_xor_b32_e32 v204, v204, v203
	v_lshlrev_b32_e32 v228, 8, v207
	v_lshl_add_u32 v228, v204, 4, v228
	v_add_u32_e32 v228, 0x1e000, v228
	v_or_b32_e32 v204, 4, v206
	v_and_b32_e32 v203, 15, v207
	v_xor_b32_e32 v204, v204, v203
	v_lshlrev_b32_e32 v227, 8, v207
	v_lshl_add_u32 v227, v204, 4, v227
	v_add_u32_e32 v227, 0x1e000, v227
	v_or_b32_e32 v204, 8, v206
	v_and_b32_e32 v203, 15, v207
	v_xor_b32_e32 v204, v204, v203
	v_lshlrev_b32_e32 v226, 8, v207
	v_lshl_add_u32 v226, v204, 4, v226
	v_add_u32_e32 v226, 0x1e000, v226
	v_or_b32_e32 v204, 12, v206
	v_and_b32_e32 v203, 15, v207
	v_xor_b32_e32 v204, v204, v203
	v_lshlrev_b32_e32 v225, 8, v207
	v_lshl_add_u32 v225, v204, 4, v225
	v_add_u32_e32 v225, 0x1e000, v225
	v_or_b32_e32 v204, 0, v206
	v_bfe_u32 v203, v207, 1, 3
	v_xor_b32_e32 v204, v204, v203
	v_lshlrev_b32_e32 v224, 7, v207
	v_lshl_add_u32 v224, v204, 4, v224
	v_add_u32_e32 v224, 0x20100, v224
	v_or_b32_e32 v204, 4, v206
	v_bfe_u32 v203, v207, 1, 3
	v_xor_b32_e32 v204, v204, v203
	v_lshlrev_b32_e32 v223, 7, v207
	v_lshl_add_u32 v223, v204, 4, v223
	v_add_u32_e32 v223, 0x20100, v223
	v_and_b32_e32 v205, 1, v163
	v_lshl_add_u32 v205, v205, 6, v207
	v_or_b32_e32 v204, 0, v206
	v_bfe_u32 v203, v205, 1, 3
	v_xor_b32_e32 v204, v204, v203
	v_lshlrev_b32_e32 v232, 7, v205
	v_lshl_add_u32 v232, v204, 4, v232
; #define LAS __attribute__((address_space(3)))
; __device__ __forceinline__ void gla_scan_item(const Ctx& C, int item, LAS unsigned char* lds, int tid) {
;     ...
;     const int wave = tid >> 6, lane = tid & 63, l15 = lane & 15, quad = lane >> 4;
;     f32x4 S[2] = {(f32x4){0.f, 0.f, 0.f, 0.f}, (f32x4){0.f, 0.f, 0.f, 0.f}};
;     *(LAS u32x4*)(Bc + (tid >> 4) * 200 + (tid & 15) * 8) = (u32x4){0u, 0u, 0u, 0u};
;     u32x4 rq0A, rq1A, rsA, rk0A, rk1A, rvA = (u32x4){0u, 0u, 0u, 0u}; f32x4 rdA;
;     u32x4 rq0B, rq1B, rsB, rk0B, rk1B, rvB = (u32x4){0u, 0u, 0u, 0u}; f32x4 rdB;
	v_add_u32_e32 v232, 0x6000, v232
	v_or_b32_e32 v204, 4, v206
	v_bfe_u32 v203, v205, 1, 3
	v_xor_b32_e32 v204, v204, v203
	v_lshlrev_b32_e32 v231, 7, v205
	v_lshl_add_u32 v231, v204, 4, v231
	v_add_u32_e32 v231, 0x6000, v231
	v_or_b32_e32 v204, 0, v206
	v_bfe_u32 v203, v207, 1, 3
	v_xor_b32_e32 v204, v204, v203
	v_lshlrev_b32_e32 v222, 7, v207
	v_lshl_add_u32 v222, v204, 4, v222
	v_add_u32_e32 v222, 0x20100, v222
	v_or_b32_e32 v204, 4, v206
	v_bfe_u32 v203, v207, 1, 3
	v_xor_b32_e32 v204, v204, v203
	v_lshlrev_b32_e32 v221, 7, v207
	v_lshl_add_u32 v221, v204, 4, v221
	v_add_u32_e32 v221, 0x20100, v221
	v_add_u32_e32 v242, 0x14000, v246
	v_add_u32_e32 v241, 0x14000, v245
	v_add_u32_e32 v240, 0x14000, v244
	v_add_u32_e32 v239, 0x14000, v243
	v_add_u32_e32 v234, 0x14000, v238
	v_add_u32_e32 v233, 0x14000, v235
	v_add_u32_e32 v230, 0x14000, v232
	v_add_u32_e32 v229, 0x14000, v231
	v_and_b32_e32 v205, 1, v163
	v_lshrrev_b32_e32 v204, 1, v206
	v_lshl_add_u32 v204, v205, 3, v204
	v_xor_b32_e32 v204, v204, v207
	v_lshlrev_b32_e32 v220, 8, v207
	v_lshl_add_u32 v220, v204, 4, v220
	v_and_b32_e32 v204, 1, v206
	v_lshl_add_u32 v220, v204, 3, v220
	v_add_u32_e32 v220, 0x1e000, v220
	v_and_b32_e32 v205, 1, v163
	v_lshrrev_b32_e32 v204, 1, v206
	v_lshl_add_u32 v204, v205, 3, v204
	v_add_u32_e32 v204, 2, v204
	v_xor_b32_e32 v204, v204, v207
	v_lshlrev_b32_e32 v219, 8, v207
	v_lshl_add_u32 v219, v204, 4, v219
	v_and_b32_e32 v204, 1, v206
	v_lshl_add_u32 v219, v204, 3, v219
	v_add_u32_e32 v219, 0x1e000, v219
	v_and_b32_e32 v205, 1, v163
	v_lshrrev_b32_e32 v204, 1, v206
	v_lshl_add_u32 v204, v205, 3, v204
	v_add_u32_e32 v204, 4, v204
	v_xor_b32_e32 v204, v204, v207
	v_lshlrev_b32_e32 v218, 8, v207
	v_lshl_add_u32 v218, v204, 4, v218
	v_and_b32_e32 v204, 1, v206
	v_lshl_add_u32 v218, v204, 3, v218
	v_add_u32_e32 v218, 0x1e000, v218
	v_and_b32_e32 v205, 1, v163
	v_lshrrev_b32_e32 v204, 1, v206
	v_lshl_add_u32 v204, v205, 3, v204
	v_add_u32_e32 v204, 6, v204
	v_xor_b32_e32 v204, v204, v207
	v_lshlrev_b32_e32 v217, 8, v207
	v_lshl_add_u32 v217, v204, 4, v217
	v_and_b32_e32 v204, 1, v206
	v_lshl_add_u32 v217, v204, 3, v217
	v_add_u32_e32 v217, 0x1e000, v217
	v_bfe_u32 v205, v162, 2, 6
	v_and_b32_e32 v203, 3, v162
	v_lshl_add_u32 v204, v203, 3, 0
	v_lshlrev_b32_e32 v216, 7, v204
	v_bfe_u32 v204, v204, 1, 3
	v_lshrrev_b32_e32 v251, 3, v205
	v_xor_b32_e32 v204, v204, v251
	v_lshl_add_u32 v216, v204, 4, v216
	v_and_b32_e32 v204, 7, v205
	v_lshl_add_u32 v216, v204, 1, v216
	v_add_u32_e32 v216, 0x20100, v216
	v_lshl_add_u32 v204, v203, 3, 1
	v_lshlrev_b32_e32 v215, 7, v204
	v_bfe_u32 v204, v204, 1, 3
	v_lshrrev_b32_e32 v251, 3, v205
	v_xor_b32_e32 v204, v204, v251
	v_lshl_add_u32 v215, v204, 4, v215
	v_and_b32_e32 v204, 7, v205
	v_lshl_add_u32 v215, v204, 1, v215
	v_add_u32_e32 v215, 0x20100, v215
	v_lshl_add_u32 v204, v203, 3, 2
	v_lshlrev_b32_e32 v214, 7, v204
	v_bfe_u32 v204, v204, 1, 3
	v_lshrrev_b32_e32 v251, 3, v205
	v_xor_b32_e32 v204, v204, v251
	v_lshl_add_u32 v214, v204, 4, v214
	v_and_b32_e32 v204, 7, v205
	v_lshl_add_u32 v214, v204, 1, v214
	v_add_u32_e32 v214, 0x20100, v214
	v_lshl_add_u32 v204, v203, 3, 3
	v_lshlrev_b32_e32 v213, 7, v204
	v_bfe_u32 v204, v204, 1, 3
	v_lshrrev_b32_e32 v251, 3, v205
	v_xor_b32_e32 v204, v204, v251
	v_lshl_add_u32 v213, v204, 4, v213
	v_and_b32_e32 v204, 7, v205
	v_lshl_add_u32 v213, v204, 1, v213
	v_add_u32_e32 v213, 0x20100, v213
	v_lshl_add_u32 v204, v203, 3, 4
	v_lshlrev_b32_e32 v212, 7, v204
	v_bfe_u32 v204, v204, 1, 3
	v_lshrrev_b32_e32 v251, 3, v205
	v_xor_b32_e32 v204, v204, v251
	v_lshl_add_u32 v212, v204, 4, v212
	v_and_b32_e32 v204, 7, v205
	v_lshl_add_u32 v212, v204, 1, v212
	v_add_u32_e32 v212, 0x20100, v212
	v_lshl_add_u32 v204, v203, 3, 5
	v_lshlrev_b32_e32 v211, 7, v204
	v_bfe_u32 v204, v204, 1, 3
	v_lshrrev_b32_e32 v251, 3, v205
	v_xor_b32_e32 v204, v204, v251
	v_lshl_add_u32 v211, v204, 4, v211
	v_and_b32_e32 v204, 7, v205
	v_lshl_add_u32 v211, v204, 1, v211
	v_add_u32_e32 v211, 0x20100, v211
	v_lshl_add_u32 v204, v203, 3, 6
	v_lshlrev_b32_e32 v210, 7, v204
	v_bfe_u32 v204, v204, 1, 3
	v_lshrrev_b32_e32 v251, 3, v205
	v_xor_b32_e32 v204, v204, v251
	v_lshl_add_u32 v210, v204, 4, v210
	v_and_b32_e32 v204, 7, v205
	v_lshl_add_u32 v210, v204, 1, v210
	v_add_u32_e32 v210, 0x20100, v210
	v_lshl_add_u32 v204, v203, 3, 7
	v_lshlrev_b32_e32 v209, 7, v204
	v_bfe_u32 v204, v204, 1, 3
	v_lshrrev_b32_e32 v251, 3, v205
	v_xor_b32_e32 v204, v204, v251
	v_lshl_add_u32 v209, v204, 4, v209
	v_and_b32_e32 v204, 7, v205
	v_lshl_add_u32 v209, v204, 1, v209
	v_add_u32_e32 v209, 0x20100, v209
	v_bfe_u32 v205, v162, 2, 6
	v_and_b32_e32 v204, 3, v162
	v_lshlrev_b32_e32 v255, 14, v205
	v_lshl_add_u32 v255, v204, 4, v255
	v_and_b32_e32 v205, 1, v163
	v_lshlrev_b32_e32 v254, 8, v205
	v_lshl_add_u32 v254, v206, 4, v254
	v_lshlrev_b32_e32 v250, 16, v205
	v_lshl_add_u32 v250, v206, 12, v250
	v_lshl_add_u32 v250, v207, 2, v250
	v_add_u32_e32 v249, 0x4000, v250
	v_add_u32_e32 v248, 0x8000, v250
	v_add_u32_e32 v247, 0xc000, v250
	v_lshlrev_b32_e32 v251, 4, v162
	v_add_u32_e32 v251, 0x1e000, v251
	v_mov_b32_e32 v8, 0
	v_mov_b32_e32 v9, 0
	v_mov_b32_e32 v10, 0
	v_mov_b32_e32 v11, 0
	v_subrev_u32_e32 v202, 40, v208
	v_cmp_gt_u32_e32 vcc, 40, v208
	v_cndmask_b32_e32 v202, v202, v208, vcc
	v_lshlrev_b32_e32 v200, 14, v208
	v_and_b32_e32 v199, 3, v208
	v_lshlrev_b32_e32 v199, 7, v199
	s_cmp_gt_u32 s32, 3
	s_cbranch_scc1 .Lp3V_entry
	s_cmp_gt_u32 s32, 1
	s_cbranch_scc1 .Lp3S_entry

.Lp3O_item:
	s_lshr_b32 s4, s3, 3
	s_and_b32 s41, s4, 7
	s_lshr_b32 s5, s4, 3
	s_and_b32 s37, s3, 7
	s_lshl_b32 s37, s37, 2
	s_add_i32 s37, s37, s5
	s_lshr_b32 s39, s37, 2
	s_and_b32 s40, s37, 3
	s_add_u32 s8, s94, 0x1d800000
	s_addc_u32 s9, s95, 0
	s_lshl_b32 s31, s39, 21
	s_add_u32 s8, s8, s31
	s_addc_u32 s9, s9, 0
	s_lshl_b32 s31, s40, 8
	s_add_u32 s8, s8, s31
	s_addc_u32 s9, s9, 0
	s_add_u32 s10, s94, 0x2f00000
	s_addc_u32 s11, s95, 0
	s_lshl_b32 s31, s37, 18
	s_add_u32 s10, s10, s31
	s_addc_u32 s11, s11, 0
	s_add_u32 s12, s94, 0x3700000
	s_addc_u32 s13, s95, 0
	s_lshl_b32 s31, s37, 19
	s_add_u32 s12, s12, s31
	s_addc_u32 s13, s13, 0
	s_add_u32 s18, s6, 0x0
	s_addc_u32 s19, s7, 0
	s_lshl_b32 s31, s39, 22
	s_add_u32 s18, s18, s31
	s_addc_u32 s19, s19, 0
	s_lshl_b32 s31, s40, 9
	s_add_u32 s18, s18, s31
	s_addc_u32 s19, s19, 0
	s_lshl_b32 s31, s41, 6
	s_add_u32 s18, s18, s31
	s_addc_u32 s19, s19, 0
	s_add_u32 s14, s94, 0xd702000
	s_addc_u32 s15, s95, 0
	s_lshl_b32 s31, s39, 25
	s_add_u32 s14, s14, s31
	s_addc_u32 s15, s15, 0
	s_lshl_b32 s31, s40, 9
	s_add_u32 s14, s14, s31
	s_addc_u32 s15, s15, 0
	s_lshl_b32 s31, s41, 6
	s_add_u32 s14, s14, s31
	s_addc_u32 s15, s15, 0
	s_add_u32 s16, s94, 0x2e00600
	s_addc_u32 s17, s95, 0
	s_lshl_b32 s31, s37, 14
	s_add_u32 s16, s16, s31
	s_addc_u32 s17, s17, 0
	s_mul_i32 s31, s41, 40
	v_add_u32_e32 v197, s31, v202
	v_subrev_u32_e32 v12, 192, v197
	v_lshlrev_b32_e32 v12, 7, v12
	v_mov_b32_e32 v203, s12
	v_mov_b32_e32 v13, s13
	v_mov_b32_e32 v201, 0x4000
	v_cmp_gt_u32_e32 vcc, 192, v197
	v_subrev_u32_e32 v205, 128, v197
	v_lshlrev_b32_e32 v205, 7, v205
	v_cndmask_b32_e32 v12, v12, v205, vcc
	v_mov_b32_e32 v205, s10
	v_cndmask_b32_e32 v203, v203, v205, vcc
	v_mov_b32_e32 v205, s11
	v_cndmask_b32_e32 v13, v13, v205, vcc
	v_mov_b32_e32 v205, 0x2000
	v_cndmask_b32_e32 v201, v201, v205, vcc
	v_cmp_gt_u32_e32 vcc, 128, v197
	v_lshrrev_b32_e32 v205, 1, v197
	v_lshlrev_b32_e32 v205, 10, v205
	v_and_b32_e32 v204, 1, v197
	v_lshl_add_u32 v205, v204, 7, v205
	v_cndmask_b32_e32 v12, v12, v205, vcc
	v_mov_b32_e32 v205, s8
	v_cndmask_b32_e32 v203, v203, v205, vcc
	v_mov_b32_e32 v205, s9
	v_cndmask_b32_e32 v13, v13, v205, vcc
	v_mov_b32_e32 v205, 0x10000
	v_cndmask_b32_e32 v201, v201, v205, vcc
	v_lshl_add_u32 v12, v201, 1, v12
	v_add_co_u32_e32 v12, vcc, v203, v12
	s_nop 1
	v_addc_co_u32_e32 v13, vcc, 0, v13, vcc
	global_load_dword v198, v[12:13], off
	global_load_dword v198, v200, s[14:15]
	global_load_dword v198, v199, s[16:17]
	v_add_co_u32_e32 v12, vcc, v201, v12
	s_add_u32 s14, s14, 0x100000
	s_addc_u32 s15, s15, 0
	v_addc_co_u32_e32 v13, vcc, 0, v13, vcc
	s_add_u32 s16, s16, 0x200
	s_addc_u32 s17, s17, 0
	global_load_dword v198, v[12:13], off
	global_load_dword v198, v200, s[14:15]
	global_load_dword v198, v199, s[16:17]
	v_add_co_u32_e32 v12, vcc, v201, v12
	s_add_u32 s14, s14, 0x100000
	s_addc_u32 s15, s15, 0
	v_addc_co_u32_e32 v13, vcc, 0, v13, vcc
	s_add_u32 s16, s16, 0x200
	s_addc_u32 s17, s17, 0
	global_load_dword v198, v[12:13], off
	global_load_dword v198, v200, s[14:15]
	global_load_dword v198, v199, s[16:17]
	v_add_co_u32_e32 v12, vcc, v201, v12
	s_add_u32 s14, s14, 0x100000
	s_addc_u32 s15, s15, 0
	v_addc_co_u32_e32 v13, vcc, 0, v13, vcc
	s_add_u32 s16, s16, 0x200
	s_addc_u32 s17, s17, 0
	ds_write_b128 v251, v[8:11]
	s_waitcnt vmcnt(0)
	s_mov_b32 s33, 0
	s_waitcnt lgkmcnt(0)
	s_barrier
.Lp3O_loop:
	ds_read_b128 v[64:67], v246 offset:0
	ds_read_b128 v[16:19], v228 offset:0
	ds_read_b128 v[20:23], v228 offset:4096
	ds_read_b128 v[68:71], v246 offset:4096
	ds_read_b128 v[72:75], v245 offset:0
	ds_read_b128 v[24:27], v227 offset:0
	ds_read_b128 v[28:31], v227 offset:4096
	ds_read_b128 v[76:79], v245 offset:4096
	ds_read_b128 v[80:83], v244 offset:0
	ds_read_b128 v[32:35], v226 offset:0
	ds_read_b128 v[36:39], v226 offset:4096
	ds_read_b128 v[84:87], v244 offset:4096
	s_cmp_gt_u32 s33, 25
	s_cbranch_scc1 .Lp3_nt1
	global_load_dword v198, v[12:13], off
	global_load_dword v198, v200, s[14:15]
	global_load_dword v198, v199, s[16:17]
	v_add_co_u32_e32 v12, vcc, v201, v12
	s_add_u32 s14, s14, 0x100000
	s_addc_u32 s15, s15, 0
	v_addc_co_u32_e32 v13, vcc, 0, v13, vcc
	s_add_u32 s16, s16, 0x200
	s_addc_u32 s17, s17, 0
.Lp3_nt1:
	s_waitcnt lgkmcnt(8)
	v_mfma_f32_16x16x32_bf16 v[112:115], v[16:19], v[64:67], 0
	v_mfma_f32_16x16x32_bf16 v[116:119], v[20:23], v[64:67], 0
	v_mfma_f32_16x16x32_bf16 v[120:123], v[16:19], v[68:71], 0
	v_mfma_f32_16x16x32_bf16 v[124:127], v[20:23], v[68:71], 0
	ds_read_b128 v[88:91], v243 offset:0
	ds_read_b128 v[40:43], v225 offset:0
	ds_read_b128 v[44:47], v225 offset:4096
	ds_read_b128 v[92:95], v243 offset:4096
	s_waitcnt lgkmcnt(8)
	v_mfma_f32_16x16x32_bf16 v[112:115], v[24:27], v[72:75], v[112:115]
	v_mfma_f32_16x16x32_bf16 v[116:119], v[28:31], v[72:75], v[116:119]
	v_mfma_f32_16x16x32_bf16 v[120:123], v[24:27], v[76:79], v[120:123]
	v_mfma_f32_16x16x32_bf16 v[124:127], v[28:31], v[76:79], v[124:127]
	ds_read_b128 v[96:99], v238 offset:0
	ds_read_b128 v[48:51], v224 offset:0
	ds_read_b128 v[52:55], v224 offset:2048
	ds_read_b128 v[100:103], v238 offset:2048
	s_waitcnt lgkmcnt(8)
	v_mfma_f32_16x16x32_bf16 v[112:115], v[32:35], v[80:83], v[112:115]
	v_mfma_f32_16x16x32_bf16 v[116:119], v[36:39], v[80:83], v[116:119]
	v_mfma_f32_16x16x32_bf16 v[120:123], v[32:35], v[84:87], v[120:123]
	v_mfma_f32_16x16x32_bf16 v[124:127], v[36:39], v[84:87], v[124:127]
	ds_read_b128 v[104:107], v235 offset:0
	ds_read_b128 v[56:59], v223 offset:0
	ds_read_b128 v[60:63], v223 offset:2048
	ds_read_b128 v[108:111], v235 offset:2048
	s_waitcnt lgkmcnt(8)
	v_mfma_f32_16x16x32_bf16 v[112:115], v[40:43], v[88:91], v[112:115]
	v_mfma_f32_16x16x32_bf16 v[116:119], v[44:47], v[88:91], v[116:119]
	v_mfma_f32_16x16x32_bf16 v[120:123], v[40:43], v[92:95], v[120:123]
	v_mfma_f32_16x16x32_bf16 v[124:127], v[44:47], v[92:95], v[124:127]
	s_waitcnt lgkmcnt(4)
	v_mfma_f32_16x16x32_bf16 v[112:115], v[48:51], v[96:99], v[112:115]
	v_mfma_f32_16x16x32_bf16 v[116:119], v[52:55], v[96:99], v[116:119]
	v_mfma_f32_16x16x32_bf16 v[120:123], v[48:51], v[100:103], v[120:123]
	v_mfma_f32_16x16x32_bf16 v[124:127], v[52:55], v[100:103], v[124:127]
	s_waitcnt lgkmcnt(0)
	v_mfma_f32_16x16x32_bf16 v[112:115], v[56:59], v[104:107], v[112:115]
	v_mfma_f32_16x16x32_bf16 v[116:119], v[60:63], v[104:107], v[116:119]
	v_mfma_f32_16x16x32_bf16 v[120:123], v[56:59], v[108:111], v[120:123]
	v_mfma_f32_16x16x32_bf16 v[124:127], v[60:63], v[108:111], v[124:127]
	s_nop 7
	s_nop 7
	v_cvt_pk_bf16_f32 v128, v112, v113
	v_cvt_pk_bf16_f32 v129, v114, v115
	v_cvt_pk_bf16_f32 v130, v116, v117
	v_cvt_pk_bf16_f32 v131, v118, v119
	v_cvt_pk_bf16_f32 v132, v120, v121
	v_cvt_pk_bf16_f32 v133, v122, v123
	v_cvt_pk_bf16_f32 v134, v124, v125
	v_cvt_pk_bf16_f32 v135, v126, v127
	global_store_dwordx2 v253, v[128:129], s[18:19]
	global_store_dwordx2 v253, v[130:131], s[18:19] offset:32
	global_store_dwordx2 v252, v[132:133], s[18:19]
	global_store_dwordx2 v252, v[134:135], s[18:19] offset:32
	s_add_u32 s18, s18, 0x20000
	s_addc_u32 s19, s19, 0
	s_add_i32 s33, s33, 1
	s_waitcnt lgkmcnt(0)
	s_barrier
	ds_read_b128 v[64:67], v246 offset:40960
	ds_read_b128 v[16:19], v228 offset:12544
	ds_read_b128 v[20:23], v228 offset:16640
	ds_read_b128 v[68:71], v246 offset:45056
	ds_read_b128 v[72:75], v245 offset:40960
	ds_read_b128 v[24:27], v227 offset:12544
	ds_read_b128 v[28:31], v227 offset:16640
	ds_read_b128 v[76:79], v245 offset:45056
	ds_read_b128 v[80:83], v244 offset:40960
	ds_read_b128 v[32:35], v226 offset:12544
	ds_read_b128 v[36:39], v226 offset:16640
	ds_read_b128 v[84:87], v244 offset:45056
	s_cmp_gt_u32 s33, 25
	s_cbranch_scc1 .Lp3_nt2
	global_load_dword v198, v[12:13], off
	global_load_dword v198, v200, s[14:15]
	global_load_dword v198, v199, s[16:17]
	v_add_co_u32_e32 v12, vcc, v201, v12
	s_add_u32 s14, s14, 0x100000
	s_addc_u32 s15, s15, 0
	v_addc_co_u32_e32 v13, vcc, 0, v13, vcc
	s_add_u32 s16, s16, 0x200
	s_addc_u32 s17, s17, 0
.Lp3_nt2:
	s_waitcnt lgkmcnt(8)
	v_mfma_f32_16x16x32_bf16 v[112:115], v[16:19], v[64:67], 0
	v_mfma_f32_16x16x32_bf16 v[116:119], v[20:23], v[64:67], 0
	v_mfma_f32_16x16x32_bf16 v[120:123], v[16:19], v[68:71], 0
	v_mfma_f32_16x16x32_bf16 v[124:127], v[20:23], v[68:71], 0
	ds_read_b128 v[88:91], v243 offset:40960
	ds_read_b128 v[40:43], v225 offset:12544
	ds_read_b128 v[44:47], v225 offset:16640
	ds_read_b128 v[92:95], v243 offset:45056
	s_waitcnt lgkmcnt(8)
	v_mfma_f32_16x16x32_bf16 v[112:115], v[24:27], v[72:75], v[112:115]
	v_mfma_f32_16x16x32_bf16 v[116:119], v[28:31], v[72:75], v[116:119]
	v_mfma_f32_16x16x32_bf16 v[120:123], v[24:27], v[76:79], v[120:123]
	v_mfma_f32_16x16x32_bf16 v[124:127], v[28:31], v[76:79], v[124:127]
	ds_read_b128 v[96:99], v238 offset:40960
	ds_read_b128 v[48:51], v224 offset:12288
	ds_read_b128 v[52:55], v224 offset:14336
	ds_read_b128 v[100:103], v238 offset:43008
	s_waitcnt lgkmcnt(8)
	v_mfma_f32_16x16x32_bf16 v[112:115], v[32:35], v[80:83], v[112:115]
	v_mfma_f32_16x16x32_bf16 v[116:119], v[36:39], v[80:83], v[116:119]
	v_mfma_f32_16x16x32_bf16 v[120:123], v[32:35], v[84:87], v[120:123]
	v_mfma_f32_16x16x32_bf16 v[124:127], v[36:39], v[84:87], v[124:127]
	ds_read_b128 v[104:107], v235 offset:40960
	ds_read_b128 v[56:59], v223 offset:12288
	ds_read_b128 v[60:63], v223 offset:14336
	ds_read_b128 v[108:111], v235 offset:43008
	s_waitcnt lgkmcnt(8)
	v_mfma_f32_16x16x32_bf16 v[112:115], v[40:43], v[88:91], v[112:115]
	v_mfma_f32_16x16x32_bf16 v[116:119], v[44:47], v[88:91], v[116:119]
	v_mfma_f32_16x16x32_bf16 v[120:123], v[40:43], v[92:95], v[120:123]
	v_mfma_f32_16x16x32_bf16 v[124:127], v[44:47], v[92:95], v[124:127]
	s_waitcnt lgkmcnt(4)
	v_mfma_f32_16x16x32_bf16 v[112:115], v[48:51], v[96:99], v[112:115]
	v_mfma_f32_16x16x32_bf16 v[116:119], v[52:55], v[96:99], v[116:119]
	v_mfma_f32_16x16x32_bf16 v[120:123], v[48:51], v[100:103], v[120:123]
	v_mfma_f32_16x16x32_bf16 v[124:127], v[52:55], v[100:103], v[124:127]
	s_waitcnt lgkmcnt(0)
	v_mfma_f32_16x16x32_bf16 v[112:115], v[56:59], v[104:107], v[112:115]
	v_mfma_f32_16x16x32_bf16 v[116:119], v[60:63], v[104:107], v[116:119]
	v_mfma_f32_16x16x32_bf16 v[120:123], v[56:59], v[108:111], v[120:123]
	v_mfma_f32_16x16x32_bf16 v[124:127], v[60:63], v[108:111], v[124:127]
	s_nop 7
	s_nop 7
	v_cvt_pk_bf16_f32 v128, v112, v113
	v_cvt_pk_bf16_f32 v129, v114, v115
	v_cvt_pk_bf16_f32 v130, v116, v117
	v_cvt_pk_bf16_f32 v131, v118, v119
	v_cvt_pk_bf16_f32 v132, v120, v121
	v_cvt_pk_bf16_f32 v133, v122, v123
	v_cvt_pk_bf16_f32 v134, v124, v125
	v_cvt_pk_bf16_f32 v135, v126, v127
	global_store_dwordx2 v253, v[128:129], s[18:19]
	global_store_dwordx2 v253, v[130:131], s[18:19] offset:32
	global_store_dwordx2 v252, v[132:133], s[18:19]
	global_store_dwordx2 v252, v[134:135], s[18:19] offset:32
	s_add_u32 s18, s18, 0x20000
	s_addc_u32 s19, s19, 0
	s_add_i32 s33, s33, 1
	s_waitcnt lgkmcnt(0)
	s_barrier
	ds_read_b128 v[64:67], v242 offset:0
	ds_read_b128 v[16:19], v228 offset:0
	ds_read_b128 v[20:23], v228 offset:4096
	ds_read_b128 v[68:71], v242 offset:4096
	ds_read_b128 v[72:75], v241 offset:0
	ds_read_b128 v[24:27], v227 offset:0
	ds_read_b128 v[28:31], v227 offset:4096
	ds_read_b128 v[76:79], v241 offset:4096
	ds_read_b128 v[80:83], v240 offset:0
	ds_read_b128 v[32:35], v226 offset:0
	ds_read_b128 v[36:39], v226 offset:4096
	ds_read_b128 v[84:87], v240 offset:4096
	s_cmp_gt_u32 s33, 25
	s_cbranch_scc1 .Lp3_nt3
	global_load_dword v198, v[12:13], off
	global_load_dword v198, v200, s[14:15]
	global_load_dword v198, v199, s[16:17]
	v_add_co_u32_e32 v12, vcc, v201, v12
	s_add_u32 s14, s14, 0x100000
	s_addc_u32 s15, s15, 0
	v_addc_co_u32_e32 v13, vcc, 0, v13, vcc
	s_add_u32 s16, s16, 0x200
	s_addc_u32 s17, s17, 0
.Lp3_nt3:
	s_waitcnt lgkmcnt(8)
	v_mfma_f32_16x16x32_bf16 v[112:115], v[16:19], v[64:67], 0
	v_mfma_f32_16x16x32_bf16 v[116:119], v[20:23], v[64:67], 0
	v_mfma_f32_16x16x32_bf16 v[120:123], v[16:19], v[68:71], 0
	v_mfma_f32_16x16x32_bf16 v[124:127], v[20:23], v[68:71], 0
	ds_read_b128 v[88:91], v239 offset:0
	ds_read_b128 v[40:43], v225 offset:0
	ds_read_b128 v[44:47], v225 offset:4096
	ds_read_b128 v[92:95], v239 offset:4096
	s_waitcnt lgkmcnt(8)
	v_mfma_f32_16x16x32_bf16 v[112:115], v[24:27], v[72:75], v[112:115]
	v_mfma_f32_16x16x32_bf16 v[116:119], v[28:31], v[72:75], v[116:119]
	v_mfma_f32_16x16x32_bf16 v[120:123], v[24:27], v[76:79], v[120:123]
	v_mfma_f32_16x16x32_bf16 v[124:127], v[28:31], v[76:79], v[124:127]
	ds_read_b128 v[96:99], v234 offset:0
	ds_read_b128 v[48:51], v224 offset:0
	ds_read_b128 v[52:55], v224 offset:2048
	ds_read_b128 v[100:103], v234 offset:2048
	s_waitcnt lgkmcnt(8)
	v_mfma_f32_16x16x32_bf16 v[112:115], v[32:35], v[80:83], v[112:115]
	v_mfma_f32_16x16x32_bf16 v[116:119], v[36:39], v[80:83], v[116:119]
	v_mfma_f32_16x16x32_bf16 v[120:123], v[32:35], v[84:87], v[120:123]
	v_mfma_f32_16x16x32_bf16 v[124:127], v[36:39], v[84:87], v[124:127]
	ds_read_b128 v[104:107], v233 offset:0
	ds_read_b128 v[56:59], v223 offset:0
	ds_read_b128 v[60:63], v223 offset:2048
	ds_read_b128 v[108:111], v233 offset:2048
	s_waitcnt lgkmcnt(8)
	v_mfma_f32_16x16x32_bf16 v[112:115], v[40:43], v[88:91], v[112:115]
	v_mfma_f32_16x16x32_bf16 v[116:119], v[44:47], v[88:91], v[116:119]
	v_mfma_f32_16x16x32_bf16 v[120:123], v[40:43], v[92:95], v[120:123]
	v_mfma_f32_16x16x32_bf16 v[124:127], v[44:47], v[92:95], v[124:127]
	s_waitcnt lgkmcnt(4)
	v_mfma_f32_16x16x32_bf16 v[112:115], v[48:51], v[96:99], v[112:115]
	v_mfma_f32_16x16x32_bf16 v[116:119], v[52:55], v[96:99], v[116:119]
	v_mfma_f32_16x16x32_bf16 v[120:123], v[48:51], v[100:103], v[120:123]
	v_mfma_f32_16x16x32_bf16 v[124:127], v[52:55], v[100:103], v[124:127]
	s_waitcnt lgkmcnt(0)
	v_mfma_f32_16x16x32_bf16 v[112:115], v[56:59], v[104:107], v[112:115]
	v_mfma_f32_16x16x32_bf16 v[116:119], v[60:63], v[104:107], v[116:119]
	v_mfma_f32_16x16x32_bf16 v[120:123], v[56:59], v[108:111], v[120:123]
	v_mfma_f32_16x16x32_bf16 v[124:127], v[60:63], v[108:111], v[124:127]
	s_nop 7
	s_nop 7
	v_cvt_pk_bf16_f32 v128, v112, v113
	v_cvt_pk_bf16_f32 v129, v114, v115
	v_cvt_pk_bf16_f32 v130, v116, v117
	v_cvt_pk_bf16_f32 v131, v118, v119
	v_cvt_pk_bf16_f32 v132, v120, v121
	v_cvt_pk_bf16_f32 v133, v122, v123
	v_cvt_pk_bf16_f32 v134, v124, v125
	v_cvt_pk_bf16_f32 v135, v126, v127
	global_store_dwordx2 v253, v[128:129], s[18:19]
	global_store_dwordx2 v253, v[130:131], s[18:19] offset:32
	global_store_dwordx2 v252, v[132:133], s[18:19]
	global_store_dwordx2 v252, v[134:135], s[18:19] offset:32
	s_add_u32 s18, s18, 0x20000
	s_addc_u32 s19, s19, 0
	s_add_i32 s33, s33, 1
	s_waitcnt lgkmcnt(0)
	s_barrier
	ds_read_b128 v[64:67], v246 offset:0
	ds_read_b128 v[16:19], v228 offset:12544
	ds_read_b128 v[20:23], v228 offset:16640
	ds_read_b128 v[68:71], v246 offset:4096
	ds_read_b128 v[72:75], v245 offset:0
	ds_read_b128 v[24:27], v227 offset:12544
	ds_read_b128 v[28:31], v227 offset:16640
	ds_read_b128 v[76:79], v245 offset:4096
	ds_read_b128 v[80:83], v244 offset:0
	ds_read_b128 v[32:35], v226 offset:12544
	ds_read_b128 v[36:39], v226 offset:16640
	ds_read_b128 v[84:87], v244 offset:4096
	s_cmp_gt_u32 s33, 25
	s_cbranch_scc1 .Lp3_nt4
	global_load_dword v198, v[12:13], off
	global_load_dword v198, v200, s[14:15]
	global_load_dword v198, v199, s[16:17]
	v_add_co_u32_e32 v12, vcc, v201, v12
	s_add_u32 s14, s14, 0x100000
	s_addc_u32 s15, s15, 0
	v_addc_co_u32_e32 v13, vcc, 0, v13, vcc
	s_add_u32 s16, s16, 0x200
	s_addc_u32 s17, s17, 0
.Lp3_nt4:
	s_waitcnt lgkmcnt(8)
	v_mfma_f32_16x16x32_bf16 v[112:115], v[16:19], v[64:67], 0
	v_mfma_f32_16x16x32_bf16 v[116:119], v[20:23], v[64:67], 0
	v_mfma_f32_16x16x32_bf16 v[120:123], v[16:19], v[68:71], 0
	v_mfma_f32_16x16x32_bf16 v[124:127], v[20:23], v[68:71], 0
	ds_read_b128 v[88:91], v243 offset:0
	ds_read_b128 v[40:43], v225 offset:12544
	ds_read_b128 v[44:47], v225 offset:16640
	ds_read_b128 v[92:95], v243 offset:4096
	s_waitcnt lgkmcnt(8)
	v_mfma_f32_16x16x32_bf16 v[112:115], v[24:27], v[72:75], v[112:115]
	v_mfma_f32_16x16x32_bf16 v[116:119], v[28:31], v[72:75], v[116:119]
	v_mfma_f32_16x16x32_bf16 v[120:123], v[24:27], v[76:79], v[120:123]
	v_mfma_f32_16x16x32_bf16 v[124:127], v[28:31], v[76:79], v[124:127]
	ds_read_b128 v[96:99], v238 offset:0
	ds_read_b128 v[48:51], v224 offset:12288
	ds_read_b128 v[52:55], v224 offset:14336
	ds_read_b128 v[100:103], v238 offset:2048
	s_waitcnt lgkmcnt(8)
	v_mfma_f32_16x16x32_bf16 v[112:115], v[32:35], v[80:83], v[112:115]
	v_mfma_f32_16x16x32_bf16 v[116:119], v[36:39], v[80:83], v[116:119]
	v_mfma_f32_16x16x32_bf16 v[120:123], v[32:35], v[84:87], v[120:123]
	v_mfma_f32_16x16x32_bf16 v[124:127], v[36:39], v[84:87], v[124:127]
	ds_read_b128 v[104:107], v235 offset:0
	ds_read_b128 v[56:59], v223 offset:12288
	ds_read_b128 v[60:63], v223 offset:14336
	ds_read_b128 v[108:111], v235 offset:2048
	s_waitcnt lgkmcnt(8)
	v_mfma_f32_16x16x32_bf16 v[112:115], v[40:43], v[88:91], v[112:115]
	v_mfma_f32_16x16x32_bf16 v[116:119], v[44:47], v[88:91], v[116:119]
	v_mfma_f32_16x16x32_bf16 v[120:123], v[40:43], v[92:95], v[120:123]
	v_mfma_f32_16x16x32_bf16 v[124:127], v[44:47], v[92:95], v[124:127]
	s_waitcnt lgkmcnt(4)
	v_mfma_f32_16x16x32_bf16 v[112:115], v[48:51], v[96:99], v[112:115]
	v_mfma_f32_16x16x32_bf16 v[116:119], v[52:55], v[96:99], v[116:119]
	v_mfma_f32_16x16x32_bf16 v[120:123], v[48:51], v[100:103], v[120:123]
	v_mfma_f32_16x16x32_bf16 v[124:127], v[52:55], v[100:103], v[124:127]
	s_waitcnt lgkmcnt(0)
	v_mfma_f32_16x16x32_bf16 v[112:115], v[56:59], v[104:107], v[112:115]
	v_mfma_f32_16x16x32_bf16 v[116:119], v[60:63], v[104:107], v[116:119]
	v_mfma_f32_16x16x32_bf16 v[120:123], v[56:59], v[108:111], v[120:123]
	v_mfma_f32_16x16x32_bf16 v[124:127], v[60:63], v[108:111], v[124:127]
	s_nop 7
	s_nop 7
	v_cvt_pk_bf16_f32 v128, v112, v113
	v_cvt_pk_bf16_f32 v129, v114, v115
	v_cvt_pk_bf16_f32 v130, v116, v117
	v_cvt_pk_bf16_f32 v131, v118, v119
	v_cvt_pk_bf16_f32 v132, v120, v121
	v_cvt_pk_bf16_f32 v133, v122, v123
	v_cvt_pk_bf16_f32 v134, v124, v125
	v_cvt_pk_bf16_f32 v135, v126, v127
	global_store_dwordx2 v253, v[128:129], s[18:19]
	global_store_dwordx2 v253, v[130:131], s[18:19] offset:32
	global_store_dwordx2 v252, v[132:133], s[18:19]
	global_store_dwordx2 v252, v[134:135], s[18:19] offset:32
	s_add_u32 s18, s18, 0x20000
	s_addc_u32 s19, s19, 0
	s_add_i32 s33, s33, 1
	s_waitcnt lgkmcnt(0)
	s_barrier
	ds_read_b128 v[64:67], v246 offset:40960
	ds_read_b128 v[16:19], v228 offset:0
	ds_read_b128 v[20:23], v228 offset:4096
	ds_read_b128 v[68:71], v246 offset:45056
	ds_read_b128 v[72:75], v245 offset:40960
	ds_read_b128 v[24:27], v227 offset:0
	ds_read_b128 v[28:31], v227 offset:4096
	ds_read_b128 v[76:79], v245 offset:45056
	ds_read_b128 v[80:83], v244 offset:40960
	ds_read_b128 v[32:35], v226 offset:0
	ds_read_b128 v[36:39], v226 offset:4096
	ds_read_b128 v[84:87], v244 offset:45056
	s_cmp_gt_u32 s33, 25
	s_cbranch_scc1 .Lp3_nt5
	global_load_dword v198, v[12:13], off
	global_load_dword v198, v200, s[14:15]
	global_load_dword v198, v199, s[16:17]
	v_add_co_u32_e32 v12, vcc, v201, v12
	s_add_u32 s14, s14, 0x100000
	s_addc_u32 s15, s15, 0
	v_addc_co_u32_e32 v13, vcc, 0, v13, vcc
	s_add_u32 s16, s16, 0x200
	s_addc_u32 s17, s17, 0
.Lp3_nt5:
	s_waitcnt lgkmcnt(8)
	v_mfma_f32_16x16x32_bf16 v[112:115], v[16:19], v[64:67], 0
	v_mfma_f32_16x16x32_bf16 v[116:119], v[20:23], v[64:67], 0
	v_mfma_f32_16x16x32_bf16 v[120:123], v[16:19], v[68:71], 0
	v_mfma_f32_16x16x32_bf16 v[124:127], v[20:23], v[68:71], 0
	ds_read_b128 v[88:91], v243 offset:40960
	ds_read_b128 v[40:43], v225 offset:0
	ds_read_b128 v[44:47], v225 offset:4096
	ds_read_b128 v[92:95], v243 offset:45056
	s_waitcnt lgkmcnt(8)
	v_mfma_f32_16x16x32_bf16 v[112:115], v[24:27], v[72:75], v[112:115]
	v_mfma_f32_16x16x32_bf16 v[116:119], v[28:31], v[72:75], v[116:119]
	v_mfma_f32_16x16x32_bf16 v[120:123], v[24:27], v[76:79], v[120:123]
	v_mfma_f32_16x16x32_bf16 v[124:127], v[28:31], v[76:79], v[124:127]
	ds_read_b128 v[96:99], v238 offset:40960
	ds_read_b128 v[48:51], v224 offset:0
	ds_read_b128 v[52:55], v224 offset:2048
	ds_read_b128 v[100:103], v238 offset:43008
	s_waitcnt lgkmcnt(8)
	v_mfma_f32_16x16x32_bf16 v[112:115], v[32:35], v[80:83], v[112:115]
	v_mfma_f32_16x16x32_bf16 v[116:119], v[36:39], v[80:83], v[116:119]
	v_mfma_f32_16x16x32_bf16 v[120:123], v[32:35], v[84:87], v[120:123]
	v_mfma_f32_16x16x32_bf16 v[124:127], v[36:39], v[84:87], v[124:127]
	ds_read_b128 v[104:107], v235 offset:40960
	ds_read_b128 v[56:59], v223 offset:0
	ds_read_b128 v[60:63], v223 offset:2048
	ds_read_b128 v[108:111], v235 offset:43008
	s_waitcnt lgkmcnt(8)
	v_mfma_f32_16x16x32_bf16 v[112:115], v[40:43], v[88:91], v[112:115]
	v_mfma_f32_16x16x32_bf16 v[116:119], v[44:47], v[88:91], v[116:119]
	v_mfma_f32_16x16x32_bf16 v[120:123], v[40:43], v[92:95], v[120:123]
	v_mfma_f32_16x16x32_bf16 v[124:127], v[44:47], v[92:95], v[124:127]
	s_waitcnt lgkmcnt(4)
	v_mfma_f32_16x16x32_bf16 v[112:115], v[48:51], v[96:99], v[112:115]
	v_mfma_f32_16x16x32_bf16 v[116:119], v[52:55], v[96:99], v[116:119]
	v_mfma_f32_16x16x32_bf16 v[120:123], v[48:51], v[100:103], v[120:123]
	v_mfma_f32_16x16x32_bf16 v[124:127], v[52:55], v[100:103], v[124:127]
	s_waitcnt lgkmcnt(0)
	v_mfma_f32_16x16x32_bf16 v[112:115], v[56:59], v[104:107], v[112:115]
	v_mfma_f32_16x16x32_bf16 v[116:119], v[60:63], v[104:107], v[116:119]
	v_mfma_f32_16x16x32_bf16 v[120:123], v[56:59], v[108:111], v[120:123]
	v_mfma_f32_16x16x32_bf16 v[124:127], v[60:63], v[108:111], v[124:127]
	s_nop 7
	s_nop 7
	v_cvt_pk_bf16_f32 v128, v112, v113
	v_cvt_pk_bf16_f32 v129, v114, v115
	v_cvt_pk_bf16_f32 v130, v116, v117
	v_cvt_pk_bf16_f32 v131, v118, v119
	v_cvt_pk_bf16_f32 v132, v120, v121
	v_cvt_pk_bf16_f32 v133, v122, v123
	v_cvt_pk_bf16_f32 v134, v124, v125
	v_cvt_pk_bf16_f32 v135, v126, v127
	global_store_dwordx2 v253, v[128:129], s[18:19]
	global_store_dwordx2 v253, v[130:131], s[18:19] offset:32
	global_store_dwordx2 v252, v[132:133], s[18:19]
	global_store_dwordx2 v252, v[134:135], s[18:19] offset:32
	s_add_u32 s18, s18, 0x20000
	s_addc_u32 s19, s19, 0
	s_add_i32 s33, s33, 1
	s_waitcnt lgkmcnt(0)
	s_barrier
	ds_read_b128 v[64:67], v242 offset:0
	ds_read_b128 v[16:19], v228 offset:12544
	ds_read_b128 v[20:23], v228 offset:16640
	ds_read_b128 v[68:71], v242 offset:4096
	ds_read_b128 v[72:75], v241 offset:0
	ds_read_b128 v[24:27], v227 offset:12544
	ds_read_b128 v[28:31], v227 offset:16640
	ds_read_b128 v[76:79], v241 offset:4096
	ds_read_b128 v[80:83], v240 offset:0
	ds_read_b128 v[32:35], v226 offset:12544
	ds_read_b128 v[36:39], v226 offset:16640
	ds_read_b128 v[84:87], v240 offset:4096
	s_cmp_gt_u32 s33, 25
	s_cbranch_scc1 .Lp3_nt6
	global_load_dword v198, v[12:13], off
	global_load_dword v198, v200, s[14:15]
	global_load_dword v198, v199, s[16:17]
	v_add_co_u32_e32 v12, vcc, v201, v12
	s_add_u32 s14, s14, 0x100000
	s_addc_u32 s15, s15, 0
	v_addc_co_u32_e32 v13, vcc, 0, v13, vcc
	s_add_u32 s16, s16, 0x200
	s_addc_u32 s17, s17, 0
.Lp3_nt6:
	s_waitcnt lgkmcnt(8)
	v_mfma_f32_16x16x32_bf16 v[112:115], v[16:19], v[64:67], 0
	v_mfma_f32_16x16x32_bf16 v[116:119], v[20:23], v[64:67], 0
	v_mfma_f32_16x16x32_bf16 v[120:123], v[16:19], v[68:71], 0
	v_mfma_f32_16x16x32_bf16 v[124:127], v[20:23], v[68:71], 0
	ds_read_b128 v[88:91], v239 offset:0
	ds_read_b128 v[40:43], v225 offset:12544
	ds_read_b128 v[44:47], v225 offset:16640
	ds_read_b128 v[92:95], v239 offset:4096
	s_waitcnt lgkmcnt(8)
	v_mfma_f32_16x16x32_bf16 v[112:115], v[24:27], v[72:75], v[112:115]
	v_mfma_f32_16x16x32_bf16 v[116:119], v[28:31], v[72:75], v[116:119]
	v_mfma_f32_16x16x32_bf16 v[120:123], v[24:27], v[76:79], v[120:123]
	v_mfma_f32_16x16x32_bf16 v[124:127], v[28:31], v[76:79], v[124:127]
	ds_read_b128 v[96:99], v234 offset:0
	ds_read_b128 v[48:51], v224 offset:12288
	ds_read_b128 v[52:55], v224 offset:14336
	ds_read_b128 v[100:103], v234 offset:2048
	s_waitcnt lgkmcnt(8)
	v_mfma_f32_16x16x32_bf16 v[112:115], v[32:35], v[80:83], v[112:115]
	v_mfma_f32_16x16x32_bf16 v[116:119], v[36:39], v[80:83], v[116:119]
	v_mfma_f32_16x16x32_bf16 v[120:123], v[32:35], v[84:87], v[120:123]
	v_mfma_f32_16x16x32_bf16 v[124:127], v[36:39], v[84:87], v[124:127]
	ds_read_b128 v[104:107], v233 offset:0
	ds_read_b128 v[56:59], v223 offset:12288
	ds_read_b128 v[60:63], v223 offset:14336
	ds_read_b128 v[108:111], v233 offset:2048
	s_waitcnt lgkmcnt(8)
	v_mfma_f32_16x16x32_bf16 v[112:115], v[40:43], v[88:91], v[112:115]
	v_mfma_f32_16x16x32_bf16 v[116:119], v[44:47], v[88:91], v[116:119]
	v_mfma_f32_16x16x32_bf16 v[120:123], v[40:43], v[92:95], v[120:123]
	v_mfma_f32_16x16x32_bf16 v[124:127], v[44:47], v[92:95], v[124:127]
	s_waitcnt lgkmcnt(4)
	v_mfma_f32_16x16x32_bf16 v[112:115], v[48:51], v[96:99], v[112:115]
	v_mfma_f32_16x16x32_bf16 v[116:119], v[52:55], v[96:99], v[116:119]
	v_mfma_f32_16x16x32_bf16 v[120:123], v[48:51], v[100:103], v[120:123]
	v_mfma_f32_16x16x32_bf16 v[124:127], v[52:55], v[100:103], v[124:127]
	s_waitcnt lgkmcnt(0)
	v_mfma_f32_16x16x32_bf16 v[112:115], v[56:59], v[104:107], v[112:115]
	v_mfma_f32_16x16x32_bf16 v[116:119], v[60:63], v[104:107], v[116:119]
	v_mfma_f32_16x16x32_bf16 v[120:123], v[56:59], v[108:111], v[120:123]
	v_mfma_f32_16x16x32_bf16 v[124:127], v[60:63], v[108:111], v[124:127]
	s_nop 7
	s_nop 7
	v_cvt_pk_bf16_f32 v128, v112, v113
	v_cvt_pk_bf16_f32 v129, v114, v115
	v_cvt_pk_bf16_f32 v130, v116, v117
	v_cvt_pk_bf16_f32 v131, v118, v119
	v_cvt_pk_bf16_f32 v132, v120, v121
	v_cvt_pk_bf16_f32 v133, v122, v123
	v_cvt_pk_bf16_f32 v134, v124, v125
	v_cvt_pk_bf16_f32 v135, v126, v127
	global_store_dwordx2 v253, v[128:129], s[18:19]
	global_store_dwordx2 v253, v[130:131], s[18:19] offset:32
	global_store_dwordx2 v252, v[132:133], s[18:19]
	global_store_dwordx2 v252, v[134:135], s[18:19] offset:32
	s_add_u32 s18, s18, 0x20000
	s_addc_u32 s19, s19, 0
	s_add_i32 s33, s33, 1
	s_waitcnt lgkmcnt(0)
	s_barrier
	s_cmp_lt_u32 s33, 30
	s_cbranch_scc1 .Lp3O_loop
	ds_read_b128 v[64:67], v246 offset:0
	ds_read_b128 v[16:19], v228 offset:0
	ds_read_b128 v[20:23], v228 offset:4096
	ds_read_b128 v[68:71], v246 offset:4096
	ds_read_b128 v[72:75], v245 offset:0
	ds_read_b128 v[24:27], v227 offset:0
	ds_read_b128 v[28:31], v227 offset:4096
	ds_read_b128 v[76:79], v245 offset:4096
	ds_read_b128 v[80:83], v244 offset:0
	ds_read_b128 v[32:35], v226 offset:0
	ds_read_b128 v[36:39], v226 offset:4096
	ds_read_b128 v[84:87], v244 offset:4096
	s_cmp_gt_u32 s33, 25
	s_cbranch_scc1 .Lp3_nt7
	global_load_dword v198, v[12:13], off
	global_load_dword v198, v200, s[14:15]
	global_load_dword v198, v199, s[16:17]
	v_add_co_u32_e32 v12, vcc, v201, v12
	s_add_u32 s14, s14, 0x100000
	s_addc_u32 s15, s15, 0
	v_addc_co_u32_e32 v13, vcc, 0, v13, vcc
	s_add_u32 s16, s16, 0x200
	s_addc_u32 s17, s17, 0

; __device__ __forceinline__ void gla_scan_item(const Ctx& C, int item, LAS unsigned char* lds, int tid) {
;     ...
;     __syncthreads();
.Lp3_nt8:
	s_waitcnt lgkmcnt(8)
	v_mfma_f32_16x16x32_bf16 v[112:115], v[16:19], v[64:67], 0
	v_mfma_f32_16x16x32_bf16 v[116:119], v[20:23], v[64:67], 0
	v_mfma_f32_16x16x32_bf16 v[120:123], v[16:19], v[68:71], 0
	v_mfma_f32_16x16x32_bf16 v[124:127], v[20:23], v[68:71], 0
	ds_read_b128 v[88:91], v243 offset:40960
	ds_read_b128 v[40:43], v225 offset:12544
	ds_read_b128 v[44:47], v225 offset:16640
	ds_read_b128 v[92:95], v243 offset:45056
	s_waitcnt lgkmcnt(8)
	v_mfma_f32_16x16x32_bf16 v[112:115], v[24:27], v[72:75], v[112:115]
	v_mfma_f32_16x16x32_bf16 v[116:119], v[28:31], v[72:75], v[116:119]
	v_mfma_f32_16x16x32_bf16 v[120:123], v[24:27], v[76:79], v[120:123]
	v_mfma_f32_16x16x32_bf16 v[124:127], v[28:31], v[76:79], v[124:127]
	ds_read_b128 v[96:99], v238 offset:40960
	ds_read_b128 v[48:51], v224 offset:12288
	ds_read_b128 v[52:55], v224 offset:14336
	ds_read_b128 v[100:103], v238 offset:43008
	s_waitcnt lgkmcnt(8)
	v_mfma_f32_16x16x32_bf16 v[112:115], v[32:35], v[80:83], v[112:115]
	v_mfma_f32_16x16x32_bf16 v[116:119], v[36:39], v[80:83], v[116:119]
	v_mfma_f32_16x16x32_bf16 v[120:123], v[32:35], v[84:87], v[120:123]
	v_mfma_f32_16x16x32_bf16 v[124:127], v[36:39], v[84:87], v[124:127]
	ds_read_b128 v[104:107], v235 offset:40960
	ds_read_b128 v[56:59], v223 offset:12288
	ds_read_b128 v[60:63], v223 offset:14336
	ds_read_b128 v[108:111], v235 offset:43008
	s_waitcnt lgkmcnt(8)
	v_mfma_f32_16x16x32_bf16 v[112:115], v[40:43], v[88:91], v[112:115]
	v_mfma_f32_16x16x32_bf16 v[116:119], v[44:47], v[88:91], v[116:119]
	v_mfma_f32_16x16x32_bf16 v[120:123], v[40:43], v[92:95], v[120:123]
	v_mfma_f32_16x16x32_bf16 v[124:127], v[44:47], v[92:95], v[124:127]
	s_waitcnt lgkmcnt(4)
	v_mfma_f32_16x16x32_bf16 v[112:115], v[48:51], v[96:99], v[112:115]
	v_mfma_f32_16x16x32_bf16 v[116:119], v[52:55], v[96:99], v[116:119]
	v_mfma_f32_16x16x32_bf16 v[120:123], v[48:51], v[100:103], v[120:123]
	v_mfma_f32_16x16x32_bf16 v[124:127], v[52:55], v[100:103], v[124:127]
	s_waitcnt lgkmcnt(0)
	v_mfma_f32_16x16x32_bf16 v[112:115], v[56:59], v[104:107], v[112:115]
	v_mfma_f32_16x16x32_bf16 v[116:119], v[60:63], v[104:107], v[116:119]
	v_mfma_f32_16x16x32_bf16 v[120:123], v[56:59], v[108:111], v[120:123]
	v_mfma_f32_16x16x32_bf16 v[124:127], v[60:63], v[108:111], v[124:127]
	s_nop 7
	s_nop 7
	v_cvt_pk_bf16_f32 v128, v112, v113
	v_cvt_pk_bf16_f32 v129, v114, v115
	v_cvt_pk_bf16_f32 v130, v116, v117
	v_cvt_pk_bf16_f32 v131, v118, v119
	v_cvt_pk_bf16_f32 v132, v120, v121
	v_cvt_pk_bf16_f32 v133, v122, v123
	v_cvt_pk_bf16_f32 v134, v124, v125
	v_cvt_pk_bf16_f32 v135, v126, v127
	global_store_dwordx2 v253, v[128:129], s[18:19]
	global_store_dwordx2 v253, v[130:131], s[18:19] offset:32
	global_store_dwordx2 v252, v[132:133], s[18:19]
	global_store_dwordx2 v252, v[134:135], s[18:19] offset:32
	s_add_u32 s18, s18, 0x20000
	s_addc_u32 s19, s19, 0
	s_add_i32 s33, s33, 1
	s_waitcnt lgkmcnt(0)
	s_barrier
	s_waitcnt vmcnt(0) lgkmcnt(0)
	s_barrier
	s_add_i32 s3, s3, s42
	s_cmpk_lt_i32 s3, 0x100
	s_cbranch_scc1 .Lp3O_item
	s_branch .Lp3_done

; #define LAS __attribute__((address_space(3)))
; __device__ __forceinline__ void gla_scan_item(const Ctx& C, int item, LAS unsigned char* lds, int tid) {
;     const int jx = item >> 3, bh = (item & 7) * 4 + (jx >> 3), sl = jx & 7, b = bh >> 2, h = bh & 3;
;     LAS bf16* Aq = (LAS bf16*)lds;
;     LAS bf16* Bc = (LAS bf16*)(lds + 25600);
;     LAS bf16* Kt = (LAS bf16*)(lds + 38400);
;     const int wave = tid >> 6, lane = tid & 63, l15 = lane & 15, quad = lane >> 4;
;     f32x4 S[2] = {(f32x4){0.f, 0.f, 0.f, 0.f}, (f32x4){0.f, 0.f, 0.f, 0.f}};
;     *(LAS u32x4*)(Bc + (tid >> 4) * 200 + (tid & 15) * 8) = (u32x4){0u, 0u, 0u, 0u};
;     u32x4 rq0A, rq1A, rsA, rk0A, rk1A, rvA = (u32x4){0u, 0u, 0u, 0u}; f32x4 rdA;
;     u32x4 rq0B, rq1B, rsB, rk0B, rk1B, rvB = (u32x4){0u, 0u, 0u, 0u}; f32x4 rdB;
.Lp3S_item:
	s_lshr_b32 s4, s3, 3
	s_and_b32 s41, s4, 7
	s_lshr_b32 s5, s4, 3
	s_and_b32 s37, s3, 7
	s_lshl_b32 s37, s37, 2
	s_add_i32 s37, s37, s5
	s_lshr_b32 s39, s37, 2
	s_and_b32 s40, s37, 3
	s_add_u32 s8, s94, 0x1d800000
	s_addc_u32 s9, s95, 0
	s_lshl_b32 s31, s39, 21
	s_add_u32 s8, s8, s31
	s_addc_u32 s9, s9, 0
	s_lshl_b32 s31, s40, 8
	s_add_u32 s8, s8, s31
	s_addc_u32 s9, s9, 0
	s_add_u32 s10, s94, 0x2f00000
	s_addc_u32 s11, s95, 0
	s_lshl_b32 s31, s37, 18
	s_add_u32 s10, s10, s31
	s_addc_u32 s11, s11, 0
	s_add_u32 s12, s94, 0x3700000
	s_addc_u32 s13, s95, 0
	s_lshl_b32 s31, s37, 19
	s_add_u32 s12, s12, s31
	s_addc_u32 s13, s13, 0
	s_add_u32 s16, s94, 0x2e00000
	s_addc_u32 s17, s95, 0
	s_lshl_b32 s31, s37, 14
	s_add_u32 s16, s16, s31
	s_addc_u32 s17, s17, 0
	s_add_u32 s34, s92, 0x4090000
	s_addc_u32 s35, s93, 0
	s_lshl_b32 s31, s37, 17
	s_add_u32 s34, s34, s31
	s_addc_u32 s35, s35, 0
	s_lshl_b32 s31, s41, 7
	s_add_u32 s34, s34, s31
	s_addc_u32 s35, s35, 0
	v_mov_b32_e32 v64, 0
	v_mov_b32_e32 v65, 0
	v_mov_b32_e32 v66, 0
	v_mov_b32_e32 v67, 0
	v_mov_b32_e32 v68, 0
	v_mov_b32_e32 v69, 0
	v_mov_b32_e32 v70, 0
	v_mov_b32_e32 v71, 0
	v_mov_b32_e32 v72, 0
	v_mov_b32_e32 v73, 0
	v_mov_b32_e32 v74, 0
	v_mov_b32_e32 v75, 0
	v_mov_b32_e32 v76, 0
	v_mov_b32_e32 v77, 0
	v_mov_b32_e32 v78, 0
	v_mov_b32_e32 v79, 0
	v_mov_b32_e32 v80, 0
	v_mov_b32_e32 v81, 0
	v_mov_b32_e32 v82, 0
	v_mov_b32_e32 v83, 0
	v_mov_b32_e32 v84, 0
	v_mov_b32_e32 v85, 0
	v_mov_b32_e32 v86, 0
	v_mov_b32_e32 v87, 0
	v_mov_b32_e32 v88, 0
	v_mov_b32_e32 v89, 0
	v_mov_b32_e32 v90, 0
	v_mov_b32_e32 v91, 0
	v_mov_b32_e32 v92, 0
	v_mov_b32_e32 v93, 0
	v_mov_b32_e32 v94, 0
	v_mov_b32_e32 v95, 0
	ds_write_b128 v251, v[8:11]
	global_load_dwordx4 v[96:99], v254, s[16:17] offset:0
	global_load_dwordx4 v[100:103], v254, s[16:17] offset:64
	global_load_dwordx4 v[104:107], v254, s[16:17] offset:128
	global_load_dwordx4 v[108:111], v254, s[16:17] offset:192
	s_add_u32 s16, s16, 0x200
	s_addc_u32 s17, s17, 0
	global_load_dwordx4 v[112:115], v254, s[16:17] offset:0
	global_load_dwordx4 v[116:119], v254, s[16:17] offset:64
	global_load_dwordx4 v[120:123], v254, s[16:17] offset:128
	global_load_dwordx4 v[124:127], v254, s[16:17] offset:192
	s_add_u32 s16, s16, 0x200
	s_addc_u32 s17, s17, 0
	global_load_dwordx4 v[128:131], v254, s[16:17] offset:0
	global_load_dwordx4 v[132:135], v254, s[16:17] offset:64
	global_load_dwordx4 v[136:139], v254, s[16:17] offset:128
	global_load_dwordx4 v[140:143], v254, s[16:17] offset:192
	s_add_u32 s16, s16, 0x200
	s_addc_u32 s17, s17, 0
	s_waitcnt vmcnt(0)
	s_mov_b32 s33, 0
	s_waitcnt lgkmcnt(0)
	s_barrier
.Lp3S_loop:
	ds_read_b128 v[48:51], v222 offset:0
	ds_read_b128 v[52:55], v222 offset:2048
	ds_read_b128 v[16:19], v232 offset:0
	ds_read_b128 v[20:23], v232 offset:2048
	ds_read_b128 v[24:27], v232 offset:4096
	ds_read_b128 v[28:31], v232 offset:6144
	ds_read_b128 v[56:59], v221 offset:0
	ds_read_b128 v[60:63], v221 offset:2048
	ds_read_b128 v[32:35], v231 offset:0
	ds_read_b128 v[36:39], v231 offset:2048
	ds_read_b128 v[40:43], v231 offset:4096
	ds_read_b128 v[44:47], v231 offset:6144
	s_waitcnt lgkmcnt(6)
	v_mfma_f32_16x16x32_bf16 v[64:67], v[16:19], v[48:51], v[64:67]
	v_mfma_f32_16x16x32_bf16 v[68:71], v[16:19], v[52:55], v[68:71]
	v_mfma_f32_16x16x32_bf16 v[72:75], v[20:23], v[48:51], v[72:75]
	v_mfma_f32_16x16x32_bf16 v[76:79], v[20:23], v[52:55], v[76:79]
	v_mfma_f32_16x16x32_bf16 v[80:83], v[24:27], v[48:51], v[80:83]
	v_mfma_f32_16x16x32_bf16 v[84:87], v[24:27], v[52:55], v[84:87]
	v_mfma_f32_16x16x32_bf16 v[88:91], v[28:31], v[48:51], v[88:91]
	v_mfma_f32_16x16x32_bf16 v[92:95], v[28:31], v[52:55], v[92:95]
	s_waitcnt lgkmcnt(0)
	v_mfma_f32_16x16x32_bf16 v[64:67], v[32:35], v[56:59], v[64:67]
	v_mfma_f32_16x16x32_bf16 v[68:71], v[32:35], v[60:63], v[68:71]
	v_mfma_f32_16x16x32_bf16 v[72:75], v[36:39], v[56:59], v[72:75]
	v_mfma_f32_16x16x32_bf16 v[76:79], v[36:39], v[60:63], v[76:79]
	v_mfma_f32_16x16x32_bf16 v[80:83], v[40:43], v[56:59], v[80:83]
	v_mfma_f32_16x16x32_bf16 v[84:87], v[40:43], v[60:63], v[84:87]
	v_mfma_f32_16x16x32_bf16 v[88:91], v[44:47], v[56:59], v[88:91]
	v_mfma_f32_16x16x32_bf16 v[92:95], v[44:47], v[60:63], v[92:95]
	s_nop 3
	global_load_dwordx4 v[96:99], v254, s[16:17] offset:0
	global_load_dwordx4 v[100:103], v254, s[16:17] offset:64
	global_load_dwordx4 v[104:107], v254, s[16:17] offset:128
	global_load_dwordx4 v[108:111], v254, s[16:17] offset:192
	s_cmp_lt_u32 s33, 28
	s_cselect_b32 s43, 0x200, 0
	s_add_u32 s16, s16, s43
	s_addc_u32 s17, s17, 0
	s_add_i32 s33, s33, 1
	s_nop 7
	s_nop 7
	v_cvt_pk_bf16_f32 v144, v64, v65
	v_cvt_pk_bf16_f32 v145, v66, v67
	ds_write_b64 v220, v[144:145] offset:12544
	v_cvt_pk_bf16_f32 v148, v68, v69
	v_cvt_pk_bf16_f32 v149, v70, v71
	ds_write_b64 v220, v[148:149] offset:16640
	s_nop 1
	v_cvt_pk_bf16_f32 v144, v72, v73
	v_cvt_pk_bf16_f32 v145, v74, v75
	ds_write_b64 v219, v[144:145] offset:12544
	v_cvt_pk_bf16_f32 v148, v76, v77
	v_cvt_pk_bf16_f32 v149, v78, v79
	ds_write_b64 v219, v[148:149] offset:16640
	s_nop 1
	v_cvt_pk_bf16_f32 v144, v80, v81
	v_cvt_pk_bf16_f32 v145, v82, v83
	ds_write_b64 v218, v[144:145] offset:12544
	v_cvt_pk_bf16_f32 v148, v84, v85
	v_cvt_pk_bf16_f32 v149, v86, v87
	ds_write_b64 v218, v[148:149] offset:16640
	s_nop 1
	v_cvt_pk_bf16_f32 v144, v88, v89
	v_cvt_pk_bf16_f32 v145, v90, v91
	ds_write_b64 v217, v[144:145] offset:12544
	v_cvt_pk_bf16_f32 v148, v92, v93
	v_cvt_pk_bf16_f32 v149, v94, v95
	ds_write_b64 v217, v[148:149] offset:16640
	s_nop 1
	s_waitcnt vmcnt(8)
	v_pk_mul_f32 v[64:65], v[64:65], v[112:113]
	v_pk_mul_f32 v[66:67], v[66:67], v[114:115]
	v_pk_mul_f32 v[68:69], v[68:69], v[112:113]
	v_pk_mul_f32 v[70:71], v[70:71], v[114:115]
	v_pk_mul_f32 v[72:73], v[72:73], v[116:117]
	v_pk_mul_f32 v[74:75], v[74:75], v[118:119]
	v_pk_mul_f32 v[76:77], v[76:77], v[116:117]
	v_pk_mul_f32 v[78:79], v[78:79], v[118:119]
	v_pk_mul_f32 v[80:81], v[80:81], v[120:121]
	v_pk_mul_f32 v[82:83], v[82:83], v[122:123]
	v_pk_mul_f32 v[84:85], v[84:85], v[120:121]
	v_pk_mul_f32 v[86:87], v[86:87], v[122:123]
	v_pk_mul_f32 v[88:89], v[88:89], v[124:125]
	v_pk_mul_f32 v[90:91], v[90:91], v[126:127]
	v_pk_mul_f32 v[92:93], v[92:93], v[124:125]
	v_pk_mul_f32 v[94:95], v[94:95], v[126:127]
	s_waitcnt lgkmcnt(0)
	s_barrier
	ds_read_b128 v[48:51], v222 offset:12288
	ds_read_b128 v[52:55], v222 offset:14336
	ds_read_b128 v[16:19], v232 offset:40960
	ds_read_b128 v[20:23], v232 offset:43008
	ds_read_b128 v[24:27], v232 offset:45056
	ds_read_b128 v[28:31], v232 offset:47104
	ds_read_b128 v[56:59], v221 offset:12288
	ds_read_b128 v[60:63], v221 offset:14336
	ds_read_b128 v[32:35], v231 offset:40960
	ds_read_b128 v[36:39], v231 offset:43008
	ds_read_b128 v[40:43], v231 offset:45056
	ds_read_b128 v[44:47], v231 offset:47104
	s_waitcnt lgkmcnt(6)
	v_mfma_f32_16x16x32_bf16 v[64:67], v[16:19], v[48:51], v[64:67]
	v_mfma_f32_16x16x32_bf16 v[68:71], v[16:19], v[52:55], v[68:71]
	v_mfma_f32_16x16x32_bf16 v[72:75], v[20:23], v[48:51], v[72:75]
	v_mfma_f32_16x16x32_bf16 v[76:79], v[20:23], v[52:55], v[76:79]
	v_mfma_f32_16x16x32_bf16 v[80:83], v[24:27], v[48:51], v[80:83]
	v_mfma_f32_16x16x32_bf16 v[84:87], v[24:27], v[52:55], v[84:87]
	v_mfma_f32_16x16x32_bf16 v[88:91], v[28:31], v[48:51], v[88:91]
	v_mfma_f32_16x16x32_bf16 v[92:95], v[28:31], v[52:55], v[92:95]
	s_waitcnt lgkmcnt(0)
	v_mfma_f32_16x16x32_bf16 v[64:67], v[32:35], v[56:59], v[64:67]
	v_mfma_f32_16x16x32_bf16 v[68:71], v[32:35], v[60:63], v[68:71]
	v_mfma_f32_16x16x32_bf16 v[72:75], v[36:39], v[56:59], v[72:75]
	v_mfma_f32_16x16x32_bf16 v[76:79], v[36:39], v[60:63], v[76:79]
	v_mfma_f32_16x16x32_bf16 v[80:83], v[40:43], v[56:59], v[80:83]
	v_mfma_f32_16x16x32_bf16 v[84:87], v[40:43], v[60:63], v[84:87]
	v_mfma_f32_16x16x32_bf16 v[88:91], v[44:47], v[56:59], v[88:91]
	v_mfma_f32_16x16x32_bf16 v[92:95], v[44:47], v[60:63], v[92:95]
	s_nop 3
	global_load_dwordx4 v[112:115], v254, s[16:17] offset:0
	global_load_dwordx4 v[116:119], v254, s[16:17] offset:64
	global_load_dwordx4 v[120:123], v254, s[16:17] offset:128
	global_load_dwordx4 v[124:127], v254, s[16:17] offset:192
	s_cmp_lt_u32 s33, 28
	s_cselect_b32 s43, 0x200, 0
	s_add_u32 s16, s16, s43
	s_addc_u32 s17, s17, 0
	s_add_i32 s33, s33, 1
	s_nop 7
	s_nop 7
	v_cvt_pk_bf16_f32 v144, v64, v65
	v_cvt_pk_bf16_f32 v145, v66, v67
	ds_write_b64 v220, v[144:145] offset:0
	v_cvt_pk_bf16_f32 v148, v68, v69
	v_cvt_pk_bf16_f32 v149, v70, v71
	ds_write_b64 v220, v[148:149] offset:4096
	s_nop 1
	v_cvt_pk_bf16_f32 v144, v72, v73
	v_cvt_pk_bf16_f32 v145, v74, v75
	ds_write_b64 v219, v[144:145] offset:0
	v_cvt_pk_bf16_f32 v148, v76, v77
	v_cvt_pk_bf16_f32 v149, v78, v79
	ds_write_b64 v219, v[148:149] offset:4096
	s_nop 1
	v_cvt_pk_bf16_f32 v144, v80, v81
	v_cvt_pk_bf16_f32 v145, v82, v83
	ds_write_b64 v218, v[144:145] offset:0
	v_cvt_pk_bf16_f32 v148, v84, v85
	v_cvt_pk_bf16_f32 v149, v86, v87
	ds_write_b64 v218, v[148:149] offset:4096
	s_nop 1
	v_cvt_pk_bf16_f32 v144, v88, v89
	v_cvt_pk_bf16_f32 v145, v90, v91
	ds_write_b64 v217, v[144:145] offset:0
	v_cvt_pk_bf16_f32 v148, v92, v93
	v_cvt_pk_bf16_f32 v149, v94, v95
	ds_write_b64 v217, v[148:149] offset:4096
	s_nop 1
	s_waitcnt vmcnt(8)
	v_pk_mul_f32 v[64:65], v[64:65], v[128:129]
	v_pk_mul_f32 v[66:67], v[66:67], v[130:131]
	v_pk_mul_f32 v[68:69], v[68:69], v[128:129]
	v_pk_mul_f32 v[70:71], v[70:71], v[130:131]
	v_pk_mul_f32 v[72:73], v[72:73], v[132:133]
	v_pk_mul_f32 v[74:75], v[74:75], v[134:135]
	v_pk_mul_f32 v[76:77], v[76:77], v[132:133]
	v_pk_mul_f32 v[78:79], v[78:79], v[134:135]
	v_pk_mul_f32 v[80:81], v[80:81], v[136:137]
	v_pk_mul_f32 v[82:83], v[82:83], v[138:139]
	v_pk_mul_f32 v[84:85], v[84:85], v[136:137]
	v_pk_mul_f32 v[86:87], v[86:87], v[138:139]
	v_pk_mul_f32 v[88:89], v[88:89], v[140:141]
	v_pk_mul_f32 v[90:91], v[90:91], v[142:143]
	v_pk_mul_f32 v[92:93], v[92:93], v[140:141]
	v_pk_mul_f32 v[94:95], v[94:95], v[142:143]
	s_waitcnt lgkmcnt(0)
	s_barrier
	ds_read_b128 v[48:51], v222 offset:0
	ds_read_b128 v[52:55], v222 offset:2048
	ds_read_b128 v[16:19], v230 offset:0
	ds_read_b128 v[20:23], v230 offset:2048
	ds_read_b128 v[24:27], v230 offset:4096
	ds_read_b128 v[28:31], v230 offset:6144
	ds_read_b128 v[56:59], v221 offset:0
	ds_read_b128 v[60:63], v221 offset:2048
	ds_read_b128 v[32:35], v229 offset:0
	ds_read_b128 v[36:39], v229 offset:2048
	ds_read_b128 v[40:43], v229 offset:4096
	ds_read_b128 v[44:47], v229 offset:6144
	s_waitcnt lgkmcnt(6)
	v_mfma_f32_16x16x32_bf16 v[64:67], v[16:19], v[48:51], v[64:67]
	v_mfma_f32_16x16x32_bf16 v[68:71], v[16:19], v[52:55], v[68:71]
	v_mfma_f32_16x16x32_bf16 v[72:75], v[20:23], v[48:51], v[72:75]
	v_mfma_f32_16x16x32_bf16 v[76:79], v[20:23], v[52:55], v[76:79]
	v_mfma_f32_16x16x32_bf16 v[80:83], v[24:27], v[48:51], v[80:83]
	v_mfma_f32_16x16x32_bf16 v[84:87], v[24:27], v[52:55], v[84:87]
	v_mfma_f32_16x16x32_bf16 v[88:91], v[28:31], v[48:51], v[88:91]
	v_mfma_f32_16x16x32_bf16 v[92:95], v[28:31], v[52:55], v[92:95]
	s_waitcnt lgkmcnt(0)
	v_mfma_f32_16x16x32_bf16 v[64:67], v[32:35], v[56:59], v[64:67]
	v_mfma_f32_16x16x32_bf16 v[68:71], v[32:35], v[60:63], v[68:71]
	v_mfma_f32_16x16x32_bf16 v[72:75], v[36:39], v[56:59], v[72:75]
	v_mfma_f32_16x16x32_bf16 v[76:79], v[36:39], v[60:63], v[76:79]
	v_mfma_f32_16x16x32_bf16 v[80:83], v[40:43], v[56:59], v[80:83]
	v_mfma_f32_16x16x32_bf16 v[84:87], v[40:43], v[60:63], v[84:87]
	v_mfma_f32_16x16x32_bf16 v[88:91], v[44:47], v[56:59], v[88:91]
	v_mfma_f32_16x16x32_bf16 v[92:95], v[44:47], v[60:63], v[92:95]
	s_nop 3
	global_load_dwordx4 v[128:131], v254, s[16:17] offset:0
	global_load_dwordx4 v[132:135], v254, s[16:17] offset:64
	global_load_dwordx4 v[136:139], v254, s[16:17] offset:128
	global_load_dwordx4 v[140:143], v254, s[16:17] offset:192
	s_cmp_lt_u32 s33, 28
	s_cselect_b32 s43, 0x200, 0
	s_add_u32 s16, s16, s43
	s_addc_u32 s17, s17, 0
	s_add_i32 s33, s33, 1
	s_nop 7
	s_nop 7
	v_cvt_pk_bf16_f32 v144, v64, v65
	v_cvt_pk_bf16_f32 v145, v66, v67
	ds_write_b64 v220, v[144:145] offset:12544
	v_cvt_pk_bf16_f32 v148, v68, v69
	v_cvt_pk_bf16_f32 v149, v70, v71
	ds_write_b64 v220, v[148:149] offset:16640
	s_nop 1
	v_cvt_pk_bf16_f32 v144, v72, v73
	v_cvt_pk_bf16_f32 v145, v74, v75
	ds_write_b64 v219, v[144:145] offset:12544
	v_cvt_pk_bf16_f32 v148, v76, v77
	v_cvt_pk_bf16_f32 v149, v78, v79
	ds_write_b64 v219, v[148:149] offset:16640
	s_nop 1
	v_cvt_pk_bf16_f32 v144, v80, v81
	v_cvt_pk_bf16_f32 v145, v82, v83
	ds_write_b64 v218, v[144:145] offset:12544
	v_cvt_pk_bf16_f32 v148, v84, v85
	v_cvt_pk_bf16_f32 v149, v86, v87
	ds_write_b64 v218, v[148:149] offset:16640
	s_nop 1
	v_cvt_pk_bf16_f32 v144, v88, v89
	v_cvt_pk_bf16_f32 v145, v90, v91
	ds_write_b64 v217, v[144:145] offset:12544
	v_cvt_pk_bf16_f32 v148, v92, v93
	v_cvt_pk_bf16_f32 v149, v94, v95
	ds_write_b64 v217, v[148:149] offset:16640
	s_nop 1
	s_waitcnt vmcnt(8)
	v_pk_mul_f32 v[64:65], v[64:65], v[96:97]
	v_pk_mul_f32 v[66:67], v[66:67], v[98:99]
	v_pk_mul_f32 v[68:69], v[68:69], v[96:97]
	v_pk_mul_f32 v[70:71], v[70:71], v[98:99]
	v_pk_mul_f32 v[72:73], v[72:73], v[100:101]
	v_pk_mul_f32 v[74:75], v[74:75], v[102:103]
	v_pk_mul_f32 v[76:77], v[76:77], v[100:101]
	v_pk_mul_f32 v[78:79], v[78:79], v[102:103]
	v_pk_mul_f32 v[80:81], v[80:81], v[104:105]
	v_pk_mul_f32 v[82:83], v[82:83], v[106:107]
	v_pk_mul_f32 v[84:85], v[84:85], v[104:105]
	v_pk_mul_f32 v[86:87], v[86:87], v[106:107]
	v_pk_mul_f32 v[88:89], v[88:89], v[108:109]
	v_pk_mul_f32 v[90:91], v[90:91], v[110:111]
	v_pk_mul_f32 v[92:93], v[92:93], v[108:109]
	v_pk_mul_f32 v[94:95], v[94:95], v[110:111]
	s_waitcnt lgkmcnt(0)
	s_barrier
	ds_read_b128 v[48:51], v222 offset:12288
	ds_read_b128 v[52:55], v222 offset:14336
	ds_read_b128 v[16:19], v232 offset:0
	ds_read_b128 v[20:23], v232 offset:2048
	ds_read_b128 v[24:27], v232 offset:4096
	ds_read_b128 v[28:31], v232 offset:6144
	ds_read_b128 v[56:59], v221 offset:12288
	ds_read_b128 v[60:63], v221 offset:14336
	ds_read_b128 v[32:35], v231 offset:0
	ds_read_b128 v[36:39], v231 offset:2048
	ds_read_b128 v[40:43], v231 offset:4096
	ds_read_b128 v[44:47], v231 offset:6144
	s_waitcnt lgkmcnt(6)
	v_mfma_f32_16x16x32_bf16 v[64:67], v[16:19], v[48:51], v[64:67]
	v_mfma_f32_16x16x32_bf16 v[68:71], v[16:19], v[52:55], v[68:71]
	v_mfma_f32_16x16x32_bf16 v[72:75], v[20:23], v[48:51], v[72:75]
	v_mfma_f32_16x16x32_bf16 v[76:79], v[20:23], v[52:55], v[76:79]
	v_mfma_f32_16x16x32_bf16 v[80:83], v[24:27], v[48:51], v[80:83]
	v_mfma_f32_16x16x32_bf16 v[84:87], v[24:27], v[52:55], v[84:87]
	v_mfma_f32_16x16x32_bf16 v[88:91], v[28:31], v[48:51], v[88:91]
	v_mfma_f32_16x16x32_bf16 v[92:95], v[28:31], v[52:55], v[92:95]
	s_waitcnt lgkmcnt(0)
	v_mfma_f32_16x16x32_bf16 v[64:67], v[32:35], v[56:59], v[64:67]
	v_mfma_f32_16x16x32_bf16 v[68:71], v[32:35], v[60:63], v[68:71]
	v_mfma_f32_16x16x32_bf16 v[72:75], v[36:39], v[56:59], v[72:75]
	v_mfma_f32_16x16x32_bf16 v[76:79], v[36:39], v[60:63], v[76:79]
	v_mfma_f32_16x16x32_bf16 v[80:83], v[40:43], v[56:59], v[80:83]
	v_mfma_f32_16x16x32_bf16 v[84:87], v[40:43], v[60:63], v[84:87]
	v_mfma_f32_16x16x32_bf16 v[88:91], v[44:47], v[56:59], v[88:91]
	v_mfma_f32_16x16x32_bf16 v[92:95], v[44:47], v[60:63], v[92:95]
	s_nop 3
	global_load_dwordx4 v[96:99], v254, s[16:17] offset:0
	global_load_dwordx4 v[100:103], v254, s[16:17] offset:64
	global_load_dwordx4 v[104:107], v254, s[16:17] offset:128
	global_load_dwordx4 v[108:111], v254, s[16:17] offset:192
	s_cmp_lt_u32 s33, 28
	s_cselect_b32 s43, 0x200, 0
	s_add_u32 s16, s16, s43
	s_addc_u32 s17, s17, 0
	s_add_i32 s33, s33, 1
	s_nop 7
	s_nop 7
	v_cvt_pk_bf16_f32 v144, v64, v65
	v_cvt_pk_bf16_f32 v145, v66, v67
	ds_write_b64 v220, v[144:145] offset:0
	v_cvt_pk_bf16_f32 v148, v68, v69
	v_cvt_pk_bf16_f32 v149, v70, v71
	ds_write_b64 v220, v[148:149] offset:4096
	s_nop 1
	v_cvt_pk_bf16_f32 v144, v72, v73
	v_cvt_pk_bf16_f32 v145, v74, v75
	ds_write_b64 v219, v[144:145] offset:0
	v_cvt_pk_bf16_f32 v148, v76, v77
	v_cvt_pk_bf16_f32 v149, v78, v79
	ds_write_b64 v219, v[148:149] offset:4096
	s_nop 1
	v_cvt_pk_bf16_f32 v144, v80, v81
	v_cvt_pk_bf16_f32 v145, v82, v83
	ds_write_b64 v218, v[144:145] offset:0
	v_cvt_pk_bf16_f32 v148, v84, v85
	v_cvt_pk_bf16_f32 v149, v86, v87
	ds_write_b64 v218, v[148:149] offset:4096
	s_nop 1
	v_cvt_pk_bf16_f32 v144, v88, v89
	v_cvt_pk_bf16_f32 v145, v90, v91
	ds_write_b64 v217, v[144:145] offset:0
	v_cvt_pk_bf16_f32 v148, v92, v93
	v_cvt_pk_bf16_f32 v149, v94, v95
	ds_write_b64 v217, v[148:149] offset:4096
	s_nop 1
	s_waitcnt vmcnt(8)
	v_pk_mul_f32 v[64:65], v[64:65], v[112:113]
	v_pk_mul_f32 v[66:67], v[66:67], v[114:115]
	v_pk_mul_f32 v[68:69], v[68:69], v[112:113]
	v_pk_mul_f32 v[70:71], v[70:71], v[114:115]
	v_pk_mul_f32 v[72:73], v[72:73], v[116:117]
	v_pk_mul_f32 v[74:75], v[74:75], v[118:119]
	v_pk_mul_f32 v[76:77], v[76:77], v[116:117]
	v_pk_mul_f32 v[78:79], v[78:79], v[118:119]
	v_pk_mul_f32 v[80:81], v[80:81], v[120:121]
	v_pk_mul_f32 v[82:83], v[82:83], v[122:123]
	v_pk_mul_f32 v[84:85], v[84:85], v[120:121]
	v_pk_mul_f32 v[86:87], v[86:87], v[122:123]
	v_pk_mul_f32 v[88:89], v[88:89], v[124:125]
	v_pk_mul_f32 v[90:91], v[90:91], v[126:127]
	v_pk_mul_f32 v[92:93], v[92:93], v[124:125]
	v_pk_mul_f32 v[94:95], v[94:95], v[126:127]
	s_waitcnt lgkmcnt(0)
	s_barrier
	ds_read_b128 v[48:51], v222 offset:0
	ds_read_b128 v[52:55], v222 offset:2048
	ds_read_b128 v[16:19], v232 offset:40960
	ds_read_b128 v[20:23], v232 offset:43008
	ds_read_b128 v[24:27], v232 offset:45056
	ds_read_b128 v[28:31], v232 offset:47104
	ds_read_b128 v[56:59], v221 offset:0
	ds_read_b128 v[60:63], v221 offset:2048
	ds_read_b128 v[32:35], v231 offset:40960
	ds_read_b128 v[36:39], v231 offset:43008
	ds_read_b128 v[40:43], v231 offset:45056
	ds_read_b128 v[44:47], v231 offset:47104
	s_waitcnt lgkmcnt(6)
	v_mfma_f32_16x16x32_bf16 v[64:67], v[16:19], v[48:51], v[64:67]
	v_mfma_f32_16x16x32_bf16 v[68:71], v[16:19], v[52:55], v[68:71]
	v_mfma_f32_16x16x32_bf16 v[72:75], v[20:23], v[48:51], v[72:75]
	v_mfma_f32_16x16x32_bf16 v[76:79], v[20:23], v[52:55], v[76:79]
	v_mfma_f32_16x16x32_bf16 v[80:83], v[24:27], v[48:51], v[80:83]
	v_mfma_f32_16x16x32_bf16 v[84:87], v[24:27], v[52:55], v[84:87]
	v_mfma_f32_16x16x32_bf16 v[88:91], v[28:31], v[48:51], v[88:91]
	v_mfma_f32_16x16x32_bf16 v[92:95], v[28:31], v[52:55], v[92:95]
	s_waitcnt lgkmcnt(0)
	v_mfma_f32_16x16x32_bf16 v[64:67], v[32:35], v[56:59], v[64:67]
	v_mfma_f32_16x16x32_bf16 v[68:71], v[32:35], v[60:63], v[68:71]
	v_mfma_f32_16x16x32_bf16 v[72:75], v[36:39], v[56:59], v[72:75]
	v_mfma_f32_16x16x32_bf16 v[76:79], v[36:39], v[60:63], v[76:79]
	v_mfma_f32_16x16x32_bf16 v[80:83], v[40:43], v[56:59], v[80:83]
	v_mfma_f32_16x16x32_bf16 v[84:87], v[40:43], v[60:63], v[84:87]
	v_mfma_f32_16x16x32_bf16 v[88:91], v[44:47], v[56:59], v[88:91]
	v_mfma_f32_16x16x32_bf16 v[92:95], v[44:47], v[60:63], v[92:95]
	s_nop 3
	global_load_dwordx4 v[112:115], v254, s[16:17] offset:0
	global_load_dwordx4 v[116:119], v254, s[16:17] offset:64
	global_load_dwordx4 v[120:123], v254, s[16:17] offset:128
	global_load_dwordx4 v[124:127], v254, s[16:17] offset:192
	s_cmp_lt_u32 s33, 28
	s_cselect_b32 s43, 0x200, 0
	s_add_u32 s16, s16, s43
	s_addc_u32 s17, s17, 0
	s_add_i32 s33, s33, 1
	s_nop 7
	s_nop 7
	v_cvt_pk_bf16_f32 v144, v64, v65
	v_cvt_pk_bf16_f32 v145, v66, v67
	ds_write_b64 v220, v[144:145] offset:12544
	v_cvt_pk_bf16_f32 v148, v68, v69
	v_cvt_pk_bf16_f32 v149, v70, v71
	ds_write_b64 v220, v[148:149] offset:16640
	s_nop 1
	v_cvt_pk_bf16_f32 v144, v72, v73
	v_cvt_pk_bf16_f32 v145, v74, v75
	ds_write_b64 v219, v[144:145] offset:12544
	v_cvt_pk_bf16_f32 v148, v76, v77
	v_cvt_pk_bf16_f32 v149, v78, v79
	ds_write_b64 v219, v[148:149] offset:16640
	s_nop 1
	v_cvt_pk_bf16_f32 v144, v80, v81
	v_cvt_pk_bf16_f32 v145, v82, v83
	ds_write_b64 v218, v[144:145] offset:12544
	v_cvt_pk_bf16_f32 v148, v84, v85
	v_cvt_pk_bf16_f32 v149, v86, v87
	ds_write_b64 v218, v[148:149] offset:16640
	s_nop 1
	v_cvt_pk_bf16_f32 v144, v88, v89
	v_cvt_pk_bf16_f32 v145, v90, v91
	ds_write_b64 v217, v[144:145] offset:12544
	v_cvt_pk_bf16_f32 v148, v92, v93
	v_cvt_pk_bf16_f32 v149, v94, v95
	ds_write_b64 v217, v[148:149] offset:16640
	s_nop 1
	s_waitcnt vmcnt(8)
	v_pk_mul_f32 v[64:65], v[64:65], v[128:129]
	v_pk_mul_f32 v[66:67], v[66:67], v[130:131]
	v_pk_mul_f32 v[68:69], v[68:69], v[128:129]
	v_pk_mul_f32 v[70:71], v[70:71], v[130:131]
	v_pk_mul_f32 v[72:73], v[72:73], v[132:133]
	v_pk_mul_f32 v[74:75], v[74:75], v[134:135]
	v_pk_mul_f32 v[76:77], v[76:77], v[132:133]
	v_pk_mul_f32 v[78:79], v[78:79], v[134:135]
	v_pk_mul_f32 v[80:81], v[80:81], v[136:137]
	v_pk_mul_f32 v[82:83], v[82:83], v[138:139]
	v_pk_mul_f32 v[84:85], v[84:85], v[136:137]
	v_pk_mul_f32 v[86:87], v[86:87], v[138:139]
	v_pk_mul_f32 v[88:89], v[88:89], v[140:141]
	v_pk_mul_f32 v[90:91], v[90:91], v[142:143]
	v_pk_mul_f32 v[92:93], v[92:93], v[140:141]
	v_pk_mul_f32 v[94:95], v[94:95], v[142:143]
	s_waitcnt lgkmcnt(0)
	s_barrier
	ds_read_b128 v[48:51], v222 offset:12288
	ds_read_b128 v[52:55], v222 offset:14336
	ds_read_b128 v[16:19], v230 offset:0
	ds_read_b128 v[20:23], v230 offset:2048
	ds_read_b128 v[24:27], v230 offset:4096
	ds_read_b128 v[28:31], v230 offset:6144
	ds_read_b128 v[56:59], v221 offset:12288
	ds_read_b128 v[60:63], v221 offset:14336
	ds_read_b128 v[32:35], v229 offset:0
	ds_read_b128 v[36:39], v229 offset:2048
	ds_read_b128 v[40:43], v229 offset:4096
	ds_read_b128 v[44:47], v229 offset:6144
	s_waitcnt lgkmcnt(6)
	v_mfma_f32_16x16x32_bf16 v[64:67], v[16:19], v[48:51], v[64:67]
	v_mfma_f32_16x16x32_bf16 v[68:71], v[16:19], v[52:55], v[68:71]
	v_mfma_f32_16x16x32_bf16 v[72:75], v[20:23], v[48:51], v[72:75]
	v_mfma_f32_16x16x32_bf16 v[76:79], v[20:23], v[52:55], v[76:79]
	v_mfma_f32_16x16x32_bf16 v[80:83], v[24:27], v[48:51], v[80:83]
	v_mfma_f32_16x16x32_bf16 v[84:87], v[24:27], v[52:55], v[84:87]
	v_mfma_f32_16x16x32_bf16 v[88:91], v[28:31], v[48:51], v[88:91]
	v_mfma_f32_16x16x32_bf16 v[92:95], v[28:31], v[52:55], v[92:95]
	s_waitcnt lgkmcnt(0)
	v_mfma_f32_16x16x32_bf16 v[64:67], v[32:35], v[56:59], v[64:67]
	v_mfma_f32_16x16x32_bf16 v[68:71], v[32:35], v[60:63], v[68:71]
	v_mfma_f32_16x16x32_bf16 v[72:75], v[36:39], v[56:59], v[72:75]
	v_mfma_f32_16x16x32_bf16 v[76:79], v[36:39], v[60:63], v[76:79]
	v_mfma_f32_16x16x32_bf16 v[80:83], v[40:43], v[56:59], v[80:83]
	v_mfma_f32_16x16x32_bf16 v[84:87], v[40:43], v[60:63], v[84:87]
	v_mfma_f32_16x16x32_bf16 v[88:91], v[44:47], v[56:59], v[88:91]
	v_mfma_f32_16x16x32_bf16 v[92:95], v[44:47], v[60:63], v[92:95]
	s_nop 3
	global_load_dwordx4 v[128:131], v254, s[16:17] offset:0
	global_load_dwordx4 v[132:135], v254, s[16:17] offset:64
	global_load_dwordx4 v[136:139], v254, s[16:17] offset:128
	global_load_dwordx4 v[140:143], v254, s[16:17] offset:192
	s_cmp_lt_u32 s33, 28
	s_cselect_b32 s43, 0x200, 0
	s_add_u32 s16, s16, s43
	s_addc_u32 s17, s17, 0
	s_add_i32 s33, s33, 1
	s_nop 7
	s_nop 7
	v_cvt_pk_bf16_f32 v144, v64, v65
	v_cvt_pk_bf16_f32 v145, v66, v67
	ds_write_b64 v220, v[144:145] offset:0
	v_cvt_pk_bf16_f32 v148, v68, v69
	v_cvt_pk_bf16_f32 v149, v70, v71
	ds_write_b64 v220, v[148:149] offset:4096
	s_nop 1
	v_cvt_pk_bf16_f32 v144, v72, v73
	v_cvt_pk_bf16_f32 v145, v74, v75
	ds_write_b64 v219, v[144:145] offset:0
	v_cvt_pk_bf16_f32 v148, v76, v77
	v_cvt_pk_bf16_f32 v149, v78, v79
	ds_write_b64 v219, v[148:149] offset:4096
	s_nop 1
	v_cvt_pk_bf16_f32 v144, v80, v81
	v_cvt_pk_bf16_f32 v145, v82, v83
	ds_write_b64 v218, v[144:145] offset:0
	v_cvt_pk_bf16_f32 v148, v84, v85
	v_cvt_pk_bf16_f32 v149, v86, v87
	ds_write_b64 v218, v[148:149] offset:4096
	s_nop 1
	v_cvt_pk_bf16_f32 v144, v88, v89
	v_cvt_pk_bf16_f32 v145, v90, v91
	ds_write_b64 v217, v[144:145] offset:0
	v_cvt_pk_bf16_f32 v148, v92, v93
	v_cvt_pk_bf16_f32 v149, v94, v95
	ds_write_b64 v217, v[148:149] offset:4096
	s_nop 1
	s_waitcnt vmcnt(8)
	v_pk_mul_f32 v[64:65], v[64:65], v[96:97]
	v_pk_mul_f32 v[66:67], v[66:67], v[98:99]
	v_pk_mul_f32 v[68:69], v[68:69], v[96:97]
	v_pk_mul_f32 v[70:71], v[70:71], v[98:99]
	v_pk_mul_f32 v[72:73], v[72:73], v[100:101]
	v_pk_mul_f32 v[74:75], v[74:75], v[102:103]
	v_pk_mul_f32 v[76:77], v[76:77], v[100:101]
	v_pk_mul_f32 v[78:79], v[78:79], v[102:103]
	v_pk_mul_f32 v[80:81], v[80:81], v[104:105]
	v_pk_mul_f32 v[82:83], v[82:83], v[106:107]
	v_pk_mul_f32 v[84:85], v[84:85], v[104:105]
	v_pk_mul_f32 v[86:87], v[86:87], v[106:107]
	v_pk_mul_f32 v[88:89], v[88:89], v[108:109]
	v_pk_mul_f32 v[90:91], v[90:91], v[110:111]
	v_pk_mul_f32 v[92:93], v[92:93], v[108:109]
	v_pk_mul_f32 v[94:95], v[94:95], v[110:111]
	s_waitcnt lgkmcnt(0)
	s_barrier
	s_cmp_lt_u32 s33, 30
	s_cbranch_scc1 .Lp3S_loop
	ds_read_b128 v[48:51], v222 offset:0
	ds_read_b128 v[52:55], v222 offset:2048
	ds_read_b128 v[16:19], v232 offset:0
	ds_read_b128 v[20:23], v232 offset:2048
	ds_read_b128 v[24:27], v232 offset:4096
	ds_read_b128 v[28:31], v232 offset:6144
	ds_read_b128 v[56:59], v221 offset:0
	ds_read_b128 v[60:63], v221 offset:2048
	ds_read_b128 v[32:35], v231 offset:0
	ds_read_b128 v[36:39], v231 offset:2048
	ds_read_b128 v[40:43], v231 offset:4096
	ds_read_b128 v[44:47], v231 offset:6144
	s_waitcnt lgkmcnt(6)
	v_mfma_f32_16x16x32_bf16 v[64:67], v[16:19], v[48:51], v[64:67]
	v_mfma_f32_16x16x32_bf16 v[68:71], v[16:19], v[52:55], v[68:71]
	v_mfma_f32_16x16x32_bf16 v[72:75], v[20:23], v[48:51], v[72:75]
	v_mfma_f32_16x16x32_bf16 v[76:79], v[20:23], v[52:55], v[76:79]
	v_mfma_f32_16x16x32_bf16 v[80:83], v[24:27], v[48:51], v[80:83]
	v_mfma_f32_16x16x32_bf16 v[84:87], v[24:27], v[52:55], v[84:87]
	v_mfma_f32_16x16x32_bf16 v[88:91], v[28:31], v[48:51], v[88:91]
	v_mfma_f32_16x16x32_bf16 v[92:95], v[28:31], v[52:55], v[92:95]
	s_waitcnt lgkmcnt(0)
	v_mfma_f32_16x16x32_bf16 v[64:67], v[32:35], v[56:59], v[64:67]
	v_mfma_f32_16x16x32_bf16 v[68:71], v[32:35], v[60:63], v[68:71]
	v_mfma_f32_16x16x32_bf16 v[72:75], v[36:39], v[56:59], v[72:75]
	v_mfma_f32_16x16x32_bf16 v[76:79], v[36:39], v[60:63], v[76:79]
	v_mfma_f32_16x16x32_bf16 v[80:83], v[40:43], v[56:59], v[80:83]
	v_mfma_f32_16x16x32_bf16 v[84:87], v[40:43], v[60:63], v[84:87]
	v_mfma_f32_16x16x32_bf16 v[88:91], v[44:47], v[56:59], v[88:91]
	v_mfma_f32_16x16x32_bf16 v[92:95], v[44:47], v[60:63], v[92:95]
	s_nop 3
	global_load_dwordx4 v[96:99], v254, s[16:17] offset:0
	global_load_dwordx4 v[100:103], v254, s[16:17] offset:64
	global_load_dwordx4 v[104:107], v254, s[16:17] offset:128
	global_load_dwordx4 v[108:111], v254, s[16:17] offset:192
	s_cmp_lt_u32 s33, 28
	s_cselect_b32 s43, 0x200, 0
	s_add_u32 s16, s16, s43
	s_addc_u32 s17, s17, 0
	s_add_i32 s33, s33, 1
	s_nop 7
	s_nop 7
	v_cvt_pk_bf16_f32 v144, v64, v65
	v_cvt_pk_bf16_f32 v145, v66, v67
	ds_write_b64 v220, v[144:145] offset:12544
	v_cvt_pk_bf16_f32 v148, v68, v69
	v_cvt_pk_bf16_f32 v149, v70, v71
	ds_write_b64 v220, v[148:149] offset:16640
	s_nop 1
	v_cvt_pk_bf16_f32 v144, v72, v73
	v_cvt_pk_bf16_f32 v145, v74, v75
	ds_write_b64 v219, v[144:145] offset:12544
	v_cvt_pk_bf16_f32 v148, v76, v77
	v_cvt_pk_bf16_f32 v149, v78, v79
	ds_write_b64 v219, v[148:149] offset:16640
	s_nop 1
	v_cvt_pk_bf16_f32 v144, v80, v81
	v_cvt_pk_bf16_f32 v145, v82, v83
	ds_write_b64 v218, v[144:145] offset:12544
	v_cvt_pk_bf16_f32 v148, v84, v85
	v_cvt_pk_bf16_f32 v149, v86, v87
	ds_write_b64 v218, v[148:149] offset:16640
	s_nop 1
	v_cvt_pk_bf16_f32 v144, v88, v89
	v_cvt_pk_bf16_f32 v145, v90, v91
	ds_write_b64 v217, v[144:145] offset:12544
	v_cvt_pk_bf16_f32 v148, v92, v93
	v_cvt_pk_bf16_f32 v149, v94, v95
	ds_write_b64 v217, v[148:149] offset:16640
	s_nop 1
	s_waitcnt vmcnt(8)
	v_pk_mul_f32 v[64:65], v[64:65], v[112:113]
	v_pk_mul_f32 v[66:67], v[66:67], v[114:115]
	v_pk_mul_f32 v[68:69], v[68:69], v[112:113]
	v_pk_mul_f32 v[70:71], v[70:71], v[114:115]
	v_pk_mul_f32 v[72:73], v[72:73], v[116:117]
	v_pk_mul_f32 v[74:75], v[74:75], v[118:119]
	v_pk_mul_f32 v[76:77], v[76:77], v[116:117]
	v_pk_mul_f32 v[78:79], v[78:79], v[118:119]
	v_pk_mul_f32 v[80:81], v[80:81], v[120:121]
	v_pk_mul_f32 v[82:83], v[82:83], v[122:123]
	v_pk_mul_f32 v[84:85], v[84:85], v[120:121]
	v_pk_mul_f32 v[86:87], v[86:87], v[122:123]
	v_pk_mul_f32 v[88:89], v[88:89], v[124:125]
	v_pk_mul_f32 v[90:91], v[90:91], v[126:127]
	v_pk_mul_f32 v[92:93], v[92:93], v[124:125]
	v_pk_mul_f32 v[94:95], v[94:95], v[126:127]
	s_waitcnt lgkmcnt(0)
	s_barrier
; __device__ __forceinline__ void gla_scan_item(const Ctx& C, int item, LAS unsigned char* lds, int tid) {
;     ...
;     float* So = C.out + OUT_GLAP + ((size_t)bh * 128 + wave * 16 + quad * 4) * 256 + sl * 32 + l15;
; #pragma unroll
;     for (int v2 = 0; v2 < 2; ++v2)
; #pragma unroll
;         for (int j = 0; j < 4; ++j) So[(size_t)j * 256 + v2 * 16] = S[v2][j];
;     __syncthreads();
	ds_read_b128 v[48:51], v222 offset:12288
	ds_read_b128 v[52:55], v222 offset:14336
	ds_read_b128 v[16:19], v232 offset:40960
	ds_read_b128 v[20:23], v232 offset:43008
	ds_read_b128 v[24:27], v232 offset:45056
	ds_read_b128 v[28:31], v232 offset:47104
	ds_read_b128 v[56:59], v221 offset:12288
	ds_read_b128 v[60:63], v221 offset:14336
	ds_read_b128 v[32:35], v231 offset:40960
	ds_read_b128 v[36:39], v231 offset:43008
	ds_read_b128 v[40:43], v231 offset:45056
	ds_read_b128 v[44:47], v231 offset:47104
	s_waitcnt lgkmcnt(6)
	v_mfma_f32_16x16x32_bf16 v[64:67], v[16:19], v[48:51], v[64:67]
	v_mfma_f32_16x16x32_bf16 v[68:71], v[16:19], v[52:55], v[68:71]
	v_mfma_f32_16x16x32_bf16 v[72:75], v[20:23], v[48:51], v[72:75]
	v_mfma_f32_16x16x32_bf16 v[76:79], v[20:23], v[52:55], v[76:79]
	v_mfma_f32_16x16x32_bf16 v[80:83], v[24:27], v[48:51], v[80:83]
	v_mfma_f32_16x16x32_bf16 v[84:87], v[24:27], v[52:55], v[84:87]
	v_mfma_f32_16x16x32_bf16 v[88:91], v[28:31], v[48:51], v[88:91]
	v_mfma_f32_16x16x32_bf16 v[92:95], v[28:31], v[52:55], v[92:95]
	s_waitcnt lgkmcnt(0)
	v_mfma_f32_16x16x32_bf16 v[64:67], v[32:35], v[56:59], v[64:67]
	v_mfma_f32_16x16x32_bf16 v[68:71], v[32:35], v[60:63], v[68:71]
	v_mfma_f32_16x16x32_bf16 v[72:75], v[36:39], v[56:59], v[72:75]
	v_mfma_f32_16x16x32_bf16 v[76:79], v[36:39], v[60:63], v[76:79]
	v_mfma_f32_16x16x32_bf16 v[80:83], v[40:43], v[56:59], v[80:83]
	v_mfma_f32_16x16x32_bf16 v[84:87], v[40:43], v[60:63], v[84:87]
	v_mfma_f32_16x16x32_bf16 v[88:91], v[44:47], v[56:59], v[88:91]
	v_mfma_f32_16x16x32_bf16 v[92:95], v[44:47], v[60:63], v[92:95]
	s_nop 3
	global_load_dwordx4 v[112:115], v254, s[16:17] offset:0
	global_load_dwordx4 v[116:119], v254, s[16:17] offset:64
	global_load_dwordx4 v[120:123], v254, s[16:17] offset:128
	global_load_dwordx4 v[124:127], v254, s[16:17] offset:192
	s_cmp_lt_u32 s33, 28
	s_cselect_b32 s43, 0x200, 0
	s_add_u32 s16, s16, s43
	s_addc_u32 s17, s17, 0
	s_add_i32 s33, s33, 1
	s_nop 7
	s_nop 7
	v_cvt_pk_bf16_f32 v144, v64, v65
	v_cvt_pk_bf16_f32 v145, v66, v67
	ds_write_b64 v220, v[144:145] offset:0
	v_cvt_pk_bf16_f32 v148, v68, v69
	v_cvt_pk_bf16_f32 v149, v70, v71
	ds_write_b64 v220, v[148:149] offset:4096
	s_nop 1
	v_cvt_pk_bf16_f32 v144, v72, v73
	v_cvt_pk_bf16_f32 v145, v74, v75
	ds_write_b64 v219, v[144:145] offset:0
	v_cvt_pk_bf16_f32 v148, v76, v77
	v_cvt_pk_bf16_f32 v149, v78, v79
	ds_write_b64 v219, v[148:149] offset:4096
	s_nop 1
	v_cvt_pk_bf16_f32 v144, v80, v81
	v_cvt_pk_bf16_f32 v145, v82, v83
	ds_write_b64 v218, v[144:145] offset:0
	v_cvt_pk_bf16_f32 v148, v84, v85
	v_cvt_pk_bf16_f32 v149, v86, v87
	ds_write_b64 v218, v[148:149] offset:4096
	s_nop 1
	v_cvt_pk_bf16_f32 v144, v88, v89
	v_cvt_pk_bf16_f32 v145, v90, v91
	ds_write_b64 v217, v[144:145] offset:0
	v_cvt_pk_bf16_f32 v148, v92, v93
	v_cvt_pk_bf16_f32 v149, v94, v95
	ds_write_b64 v217, v[148:149] offset:4096
	s_nop 1
	s_waitcnt lgkmcnt(0)
	s_barrier
	s_nop 7
	global_store_dword v250, v64, s[34:35] offset:0
	global_store_dword v250, v65, s[34:35] offset:1024
	global_store_dword v250, v66, s[34:35] offset:2048
	global_store_dword v250, v67, s[34:35] offset:3072
	global_store_dword v250, v68, s[34:35] offset:64
	global_store_dword v250, v69, s[34:35] offset:1088
	global_store_dword v250, v70, s[34:35] offset:2112
	global_store_dword v250, v71, s[34:35] offset:3136
	global_store_dword v249, v72, s[34:35] offset:0
	global_store_dword v249, v73, s[34:35] offset:1024
	global_store_dword v249, v74, s[34:35] offset:2048
	global_store_dword v249, v75, s[34:35] offset:3072
	global_store_dword v249, v76, s[34:35] offset:64
	global_store_dword v249, v77, s[34:35] offset:1088
	global_store_dword v249, v78, s[34:35] offset:2112
	global_store_dword v249, v79, s[34:35] offset:3136
	global_store_dword v248, v80, s[34:35] offset:0
	global_store_dword v248, v81, s[34:35] offset:1024
	global_store_dword v248, v82, s[34:35] offset:2048
	global_store_dword v248, v83, s[34:35] offset:3072
	global_store_dword v248, v84, s[34:35] offset:64
	global_store_dword v248, v85, s[34:35] offset:1088
	global_store_dword v248, v86, s[34:35] offset:2112
	global_store_dword v248, v87, s[34:35] offset:3136
	global_store_dword v247, v88, s[34:35] offset:0
	global_store_dword v247, v89, s[34:35] offset:1024
	global_store_dword v247, v90, s[34:35] offset:2048
	global_store_dword v247, v91, s[34:35] offset:3072
	global_store_dword v247, v92, s[34:35] offset:64
	global_store_dword v247, v93, s[34:35] offset:1088
	global_store_dword v247, v94, s[34:35] offset:2112
	global_store_dword v247, v95, s[34:35] offset:3136
	s_waitcnt vmcnt(0) lgkmcnt(0)
	s_barrier
	s_add_i32 s3, s3, s42
	s_cmpk_lt_i32 s3, 0x100
	s_cbranch_scc1 .Lp3S_item
	s_branch .Lp3_done

.Lp3V_item:
	s_lshr_b32 s4, s3, 3
	s_and_b32 s41, s4, 7
	s_lshr_b32 s5, s4, 3
	s_and_b32 s37, s3, 7
	s_lshl_b32 s37, s37, 2
	s_add_i32 s37, s37, s5
	s_lshr_b32 s39, s37, 2
	s_and_b32 s40, s37, 3
	s_add_u32 s8, s94, 0x1d800000
	s_addc_u32 s9, s95, 0
	s_lshl_b32 s31, s39, 21
	s_add_u32 s8, s8, s31
	s_addc_u32 s9, s9, 0
	s_lshl_b32 s31, s40, 8
	s_add_u32 s8, s8, s31
	s_addc_u32 s9, s9, 0
	s_add_u32 s10, s94, 0x2f00000
	s_addc_u32 s11, s95, 0
	s_lshl_b32 s31, s37, 18
	s_add_u32 s10, s10, s31
	s_addc_u32 s11, s11, 0
	s_add_u32 s12, s94, 0x3700000
	s_addc_u32 s13, s95, 0
	s_lshl_b32 s31, s37, 19
	s_add_u32 s12, s12, s31
	s_addc_u32 s13, s13, 0
	s_add_u32 s14, s94, 0xd402000
	s_addc_u32 s15, s95, 0
	s_lshl_b32 s31, s39, 25
	s_add_u32 s14, s14, s31
	s_addc_u32 s15, s15, 0
	s_lshl_b32 s31, s40, 9
	s_add_u32 s14, s14, s31
	s_addc_u32 s15, s15, 0
	s_lshl_b32 s31, s41, 6
	s_add_u32 s14, s14, s31
	s_addc_u32 s15, s15, 0
	ds_write_b128 v251, v[8:11]
	s_mov_b32 m0, s46
	s_nop 0
	global_load_lds_dwordx4 v195, s[8:9]
	s_add_i32 m0, s46, 0x400
	s_nop 0
	global_load_lds_dwordx4 v194, s[8:9]
	s_mov_b32 m0, s47
	s_nop 0
	global_load_lds_dwordx4 v191, s[10:11]
	s_mov_b32 m0, s48
	s_nop 0
	global_load_lds_dwordx4 v189, s[12:13]
	s_add_i32 m0, s48, 0x400
	s_nop 0
	global_load_lds_dwordx4 v188, s[12:13]
	s_add_i32 m0, s46, 0x800
	s_nop 0
	global_load_lds_dwordx4 v193, s[8:9]
	s_add_i32 m0, s46, 0xc00
	s_nop 0
	global_load_lds_dwordx4 v192, s[8:9]
	s_add_i32 m0, s47, 0x400
	s_nop 0
	global_load_lds_dwordx4 v190, s[10:11]
	s_add_i32 m0, s48, 0x800
	s_nop 0
	global_load_lds_dwordx4 v187, s[12:13]
	s_add_i32 m0, s48, 0xc00
	s_nop 0
	global_load_lds_dwordx4 v186, s[12:13]
	s_add_u32 s8, s8, 0x10000
	s_addc_u32 s9, s9, 0
	s_add_u32 s10, s10, 0x2000
	s_addc_u32 s11, s11, 0
	s_add_u32 s12, s12, 0x4000
	s_addc_u32 s13, s13, 0
	s_add_i32 m0, s46, 0xa000
	s_nop 0
	global_load_lds_dwordx4 v195, s[8:9]
	s_add_i32 m0, s46, 0xa400
	s_nop 0
	global_load_lds_dwordx4 v194, s[8:9]
	s_add_i32 m0, s47, 0xa000
	s_nop 0
	global_load_lds_dwordx4 v191, s[10:11]
	s_add_i32 m0, s48, 0xa000
	s_nop 0
	global_load_lds_dwordx4 v189, s[12:13]
	s_add_i32 m0, s48, 0xa400
	s_nop 0
	global_load_lds_dwordx4 v188, s[12:13]
	s_add_i32 m0, s46, 0xa800
	s_nop 0
	global_load_lds_dwordx4 v193, s[8:9]
	s_add_i32 m0, s46, 0xac00
	s_nop 0
	global_load_lds_dwordx4 v192, s[8:9]
	s_add_i32 m0, s47, 0xa400
	s_nop 0
	global_load_lds_dwordx4 v190, s[10:11]
	s_add_i32 m0, s48, 0xa800
	s_nop 0
	global_load_lds_dwordx4 v187, s[12:13]
	s_add_i32 m0, s48, 0xac00
	s_nop 0
	global_load_lds_dwordx4 v186, s[12:13]
	s_add_u32 s8, s8, 0x10000
	s_addc_u32 s9, s9, 0
	s_add_u32 s10, s10, 0x2000
	s_addc_u32 s11, s11, 0
	s_add_u32 s12, s12, 0x4000
	s_addc_u32 s13, s13, 0
	global_load_dwordx4 v[16:19], v255, s[14:15]
	s_add_u32 s14, s14, 0x100000
	s_addc_u32 s15, s15, 0
	global_load_dwordx4 v[20:23], v255, s[14:15]
	s_add_u32 s14, s14, 0x100000
	s_addc_u32 s15, s15, 0
	global_load_dwordx4 v[24:27], v255, s[14:15]
	s_add_u32 s14, s14, 0x100000
	s_addc_u32 s15, s15, 0
	s_waitcnt vmcnt(0)
	ds_write_b16 v216, v16 offset:0
	ds_write_b16_d16_hi v215, v16 offset:0
	ds_write_b16 v214, v17 offset:0
	ds_write_b16_d16_hi v213, v17 offset:0
	ds_write_b16 v212, v18 offset:0
	ds_write_b16_d16_hi v211, v18 offset:0
	ds_write_b16 v210, v19 offset:0
	ds_write_b16_d16_hi v209, v19 offset:0
	s_mov_b32 s33, 0
	s_waitcnt lgkmcnt(0)
	s_barrier
.Lp3V_loop:
	s_waitcnt vmcnt(11)
	ds_write_b16 v216, v20 offset:12288
	ds_write_b16_d16_hi v215, v20 offset:12288
	ds_write_b16 v214, v21 offset:12288
	ds_write_b16_d16_hi v213, v21 offset:12288
	ds_write_b16 v212, v22 offset:12288
	ds_write_b16_d16_hi v211, v22 offset:12288
	ds_write_b16 v210, v23 offset:12288
	ds_write_b16_d16_hi v209, v23 offset:12288
	s_add_i32 m0, s46, 0x14000
	s_nop 0
	global_load_lds_dwordx4 v195, s[8:9]
	s_add_i32 m0, s46, 0x14400
	s_nop 0
	global_load_lds_dwordx4 v194, s[8:9]
	s_add_i32 m0, s47, 0x14000
	s_nop 0
	global_load_lds_dwordx4 v191, s[10:11]
	s_add_i32 m0, s48, 0x14000
	s_nop 0
	global_load_lds_dwordx4 v189, s[12:13]
	s_add_i32 m0, s48, 0x14400
	s_nop 0
	global_load_lds_dwordx4 v188, s[12:13]
	s_add_i32 m0, s46, 0x14800
	s_nop 0
	global_load_lds_dwordx4 v193, s[8:9]
	s_add_i32 m0, s46, 0x14c00
	s_nop 0
	global_load_lds_dwordx4 v192, s[8:9]
	s_add_i32 m0, s47, 0x14400
	s_nop 0
	global_load_lds_dwordx4 v190, s[10:11]
	s_add_i32 m0, s48, 0x14800
	s_nop 0
	global_load_lds_dwordx4 v187, s[12:13]
	s_add_i32 m0, s48, 0x14c00
	s_nop 0
	global_load_lds_dwordx4 v186, s[12:13]
	s_cmp_lt_u32 s33, 29
	s_cselect_b32 s43, 0x10000, 0
	s_add_u32 s8, s8, s43
	s_addc_u32 s9, s9, 0
	s_cmp_lt_u32 s33, 29
	s_cselect_b32 s43, 0x2000, 0
	s_add_u32 s10, s10, s43
	s_addc_u32 s11, s11, 0
	s_cmp_lt_u32 s33, 29
	s_cselect_b32 s43, 0x4000, 0
	s_add_u32 s12, s12, s43
	s_addc_u32 s13, s13, 0
	global_load_dwordx4 v[16:19], v255, s[14:15]
	s_cmp_lt_u32 s33, 28
	s_cselect_b32 s43, 0x100000, 0
	s_add_u32 s14, s14, s43
	s_addc_u32 s15, s15, 0
	s_add_i32 s33, s33, 1
	s_waitcnt vmcnt(12)
	s_waitcnt lgkmcnt(0)
	s_barrier
	s_waitcnt vmcnt(11)
	ds_write_b16 v216, v24 offset:0
	ds_write_b16_d16_hi v215, v24 offset:0
	ds_write_b16 v214, v25 offset:0
	ds_write_b16_d16_hi v213, v25 offset:0
	ds_write_b16 v212, v26 offset:0
	ds_write_b16_d16_hi v211, v26 offset:0
	ds_write_b16 v210, v27 offset:0
	ds_write_b16_d16_hi v209, v27 offset:0
	s_mov_b32 m0, s46
	s_nop 0
	global_load_lds_dwordx4 v195, s[8:9]
	s_add_i32 m0, s46, 0x400
	s_nop 0
	global_load_lds_dwordx4 v194, s[8:9]
	s_mov_b32 m0, s47
	s_nop 0
	global_load_lds_dwordx4 v191, s[10:11]
	s_mov_b32 m0, s48
	s_nop 0
	global_load_lds_dwordx4 v189, s[12:13]
	s_add_i32 m0, s48, 0x400
	s_nop 0
	global_load_lds_dwordx4 v188, s[12:13]
	s_add_i32 m0, s46, 0x800
	s_nop 0
	global_load_lds_dwordx4 v193, s[8:9]
	s_add_i32 m0, s46, 0xc00
	s_nop 0
	global_load_lds_dwordx4 v192, s[8:9]
	s_add_i32 m0, s47, 0x400
	s_nop 0
	global_load_lds_dwordx4 v190, s[10:11]
	s_add_i32 m0, s48, 0x800
	s_nop 0
	global_load_lds_dwordx4 v187, s[12:13]
	s_add_i32 m0, s48, 0xc00
	s_nop 0
	global_load_lds_dwordx4 v186, s[12:13]
	s_cmp_lt_u32 s33, 29
	s_cselect_b32 s43, 0x10000, 0
	s_add_u32 s8, s8, s43
	s_addc_u32 s9, s9, 0
	s_cmp_lt_u32 s33, 29
	s_cselect_b32 s43, 0x2000, 0
	s_add_u32 s10, s10, s43
	s_addc_u32 s11, s11, 0
	s_cmp_lt_u32 s33, 29
	s_cselect_b32 s43, 0x4000, 0
	s_add_u32 s12, s12, s43
	s_addc_u32 s13, s13, 0
	global_load_dwordx4 v[20:23], v255, s[14:15]
	s_cmp_lt_u32 s33, 28
	s_cselect_b32 s43, 0x100000, 0
	s_add_u32 s14, s14, s43
	s_addc_u32 s15, s15, 0
	s_add_i32 s33, s33, 1
	s_waitcnt vmcnt(12)
	s_waitcnt lgkmcnt(0)
	s_barrier
	s_waitcnt vmcnt(11)
	ds_write_b16 v216, v16 offset:12288
	ds_write_b16_d16_hi v215, v16 offset:12288
	ds_write_b16 v214, v17 offset:12288
	ds_write_b16_d16_hi v213, v17 offset:12288
	ds_write_b16 v212, v18 offset:12288
	ds_write_b16_d16_hi v211, v18 offset:12288
	ds_write_b16 v210, v19 offset:12288
	ds_write_b16_d16_hi v209, v19 offset:12288
	s_add_i32 m0, s46, 0xa000
	s_nop 0
	global_load_lds_dwordx4 v195, s[8:9]
	s_add_i32 m0, s46, 0xa400
	s_nop 0
	global_load_lds_dwordx4 v194, s[8:9]
	s_add_i32 m0, s47, 0xa000
	s_nop 0
	global_load_lds_dwordx4 v191, s[10:11]
	s_add_i32 m0, s48, 0xa000
	s_nop 0
	global_load_lds_dwordx4 v189, s[12:13]
	s_add_i32 m0, s48, 0xa400
	s_nop 0
	global_load_lds_dwordx4 v188, s[12:13]
	s_add_i32 m0, s46, 0xa800
	s_nop 0
	global_load_lds_dwordx4 v193, s[8:9]
	s_add_i32 m0, s46, 0xac00
	s_nop 0
	global_load_lds_dwordx4 v192, s[8:9]
	s_add_i32 m0, s47, 0xa400
	s_nop 0
	global_load_lds_dwordx4 v190, s[10:11]
	s_add_i32 m0, s48, 0xa800
	s_nop 0
	global_load_lds_dwordx4 v187, s[12:13]
	s_add_i32 m0, s48, 0xac00
	s_nop 0
	global_load_lds_dwordx4 v186, s[12:13]
	s_cmp_lt_u32 s33, 29
	s_cselect_b32 s43, 0x10000, 0
	s_add_u32 s8, s8, s43
	s_addc_u32 s9, s9, 0
	s_cmp_lt_u32 s33, 29
	s_cselect_b32 s43, 0x2000, 0
	s_add_u32 s10, s10, s43
	s_addc_u32 s11, s11, 0
	s_cmp_lt_u32 s33, 29
	s_cselect_b32 s43, 0x4000, 0
	s_add_u32 s12, s12, s43
	s_addc_u32 s13, s13, 0
	global_load_dwordx4 v[24:27], v255, s[14:15]
	s_cmp_lt_u32 s33, 28
	s_cselect_b32 s43, 0x100000, 0
	s_add_u32 s14, s14, s43
	s_addc_u32 s15, s15, 0
	s_add_i32 s33, s33, 1
	s_waitcnt vmcnt(12)
	s_waitcnt lgkmcnt(0)
	s_barrier
	s_waitcnt vmcnt(11)
	ds_write_b16 v216, v20 offset:0
	ds_write_b16_d16_hi v215, v20 offset:0
	ds_write_b16 v214, v21 offset:0
	ds_write_b16_d16_hi v213, v21 offset:0
	ds_write_b16 v212, v22 offset:0
	ds_write_b16_d16_hi v211, v22 offset:0
	ds_write_b16 v210, v23 offset:0
	ds_write_b16_d16_hi v209, v23 offset:0
	s_add_i32 m0, s46, 0x14000
	s_nop 0
	global_load_lds_dwordx4 v195, s[8:9]
	s_add_i32 m0, s46, 0x14400
	s_nop 0
	global_load_lds_dwordx4 v194, s[8:9]
	s_add_i32 m0, s47, 0x14000
	s_nop 0
	global_load_lds_dwordx4 v191, s[10:11]
	s_add_i32 m0, s48, 0x14000
	s_nop 0
	global_load_lds_dwordx4 v189, s[12:13]
	s_add_i32 m0, s48, 0x14400
	s_nop 0
	global_load_lds_dwordx4 v188, s[12:13]
	s_add_i32 m0, s46, 0x14800
	s_nop 0
	global_load_lds_dwordx4 v193, s[8:9]
	s_add_i32 m0, s46, 0x14c00
	s_nop 0
	global_load_lds_dwordx4 v192, s[8:9]
	s_add_i32 m0, s47, 0x14400
	s_nop 0
	global_load_lds_dwordx4 v190, s[10:11]
	s_add_i32 m0, s48, 0x14800
	s_nop 0
	global_load_lds_dwordx4 v187, s[12:13]
	s_add_i32 m0, s48, 0x14c00
	s_nop 0
	global_load_lds_dwordx4 v186, s[12:13]
	s_cmp_lt_u32 s33, 29
	s_cselect_b32 s43, 0x10000, 0
	s_add_u32 s8, s8, s43
	s_addc_u32 s9, s9, 0
	s_cmp_lt_u32 s33, 29
	s_cselect_b32 s43, 0x2000, 0
	s_add_u32 s10, s10, s43
	s_addc_u32 s11, s11, 0
	s_cmp_lt_u32 s33, 29
	s_cselect_b32 s43, 0x4000, 0
	s_add_u32 s12, s12, s43
	s_addc_u32 s13, s13, 0
	global_load_dwordx4 v[16:19], v255, s[14:15]
	s_cmp_lt_u32 s33, 28
	s_cselect_b32 s43, 0x100000, 0
	s_add_u32 s14, s14, s43
	s_addc_u32 s15, s15, 0
	s_add_i32 s33, s33, 1
	s_waitcnt vmcnt(12)
	s_waitcnt lgkmcnt(0)
	s_barrier
	s_waitcnt vmcnt(11)
	ds_write_b16 v216, v24 offset:12288
	ds_write_b16_d16_hi v215, v24 offset:12288
	ds_write_b16 v214, v25 offset:12288
	ds_write_b16_d16_hi v213, v25 offset:12288
	ds_write_b16 v212, v26 offset:12288
	ds_write_b16_d16_hi v211, v26 offset:12288
	ds_write_b16 v210, v27 offset:12288
	ds_write_b16_d16_hi v209, v27 offset:12288
	s_mov_b32 m0, s46
	s_nop 0
	global_load_lds_dwordx4 v195, s[8:9]
	s_add_i32 m0, s46, 0x400
	s_nop 0
	global_load_lds_dwordx4 v194, s[8:9]
	s_mov_b32 m0, s47
	s_nop 0
	global_load_lds_dwordx4 v191, s[10:11]
	s_mov_b32 m0, s48
	s_nop 0
	global_load_lds_dwordx4 v189, s[12:13]
	s_add_i32 m0, s48, 0x400
	s_nop 0
	global_load_lds_dwordx4 v188, s[12:13]
	s_add_i32 m0, s46, 0x800
	s_nop 0
	global_load_lds_dwordx4 v193, s[8:9]
	s_add_i32 m0, s46, 0xc00
	s_nop 0
	global_load_lds_dwordx4 v192, s[8:9]
	s_add_i32 m0, s47, 0x400
	s_nop 0
	global_load_lds_dwordx4 v190, s[10:11]
	s_add_i32 m0, s48, 0x800
	s_nop 0
	global_load_lds_dwordx4 v187, s[12:13]
	s_add_i32 m0, s48, 0xc00
	s_nop 0
	global_load_lds_dwordx4 v186, s[12:13]
	s_cmp_lt_u32 s33, 29
	s_cselect_b32 s43, 0x10000, 0
	s_add_u32 s8, s8, s43
	s_addc_u32 s9, s9, 0
	s_cmp_lt_u32 s33, 29
	s_cselect_b32 s43, 0x2000, 0
	s_add_u32 s10, s10, s43
	s_addc_u32 s11, s11, 0
	s_cmp_lt_u32 s33, 29
	s_cselect_b32 s43, 0x4000, 0
	s_add_u32 s12, s12, s43
	s_addc_u32 s13, s13, 0
	global_load_dwordx4 v[20:23], v255, s[14:15]
	s_cmp_lt_u32 s33, 28
	s_cselect_b32 s43, 0x100000, 0
	s_add_u32 s14, s14, s43
	s_addc_u32 s15, s15, 0
	s_add_i32 s33, s33, 1
	s_waitcnt vmcnt(12)
	s_waitcnt lgkmcnt(0)
	s_barrier
; __device__ __forceinline__ void gla_scan_item(const Ctx& C, int item, LAS unsigned char* lds, int tid) {
;     ...
;     __syncthreads();
	s_waitcnt vmcnt(11)
	ds_write_b16 v216, v16 offset:0
	ds_write_b16_d16_hi v215, v16 offset:0
	ds_write_b16 v214, v17 offset:0
	ds_write_b16_d16_hi v213, v17 offset:0
	ds_write_b16 v212, v18 offset:0
	ds_write_b16_d16_hi v211, v18 offset:0
	ds_write_b16 v210, v19 offset:0
	ds_write_b16_d16_hi v209, v19 offset:0
	s_add_i32 m0, s46, 0xa000
	s_nop 0
	global_load_lds_dwordx4 v195, s[8:9]
	s_add_i32 m0, s46, 0xa400
	s_nop 0
	global_load_lds_dwordx4 v194, s[8:9]
	s_add_i32 m0, s47, 0xa000
	s_nop 0
	global_load_lds_dwordx4 v191, s[10:11]
	s_add_i32 m0, s48, 0xa000
	s_nop 0
	global_load_lds_dwordx4 v189, s[12:13]
	s_add_i32 m0, s48, 0xa400
	s_nop 0
	global_load_lds_dwordx4 v188, s[12:13]
	s_add_i32 m0, s46, 0xa800
	s_nop 0
	global_load_lds_dwordx4 v193, s[8:9]
	s_add_i32 m0, s46, 0xac00
	s_nop 0
	global_load_lds_dwordx4 v192, s[8:9]
	s_add_i32 m0, s47, 0xa400
	s_nop 0
	global_load_lds_dwordx4 v190, s[10:11]
	s_add_i32 m0, s48, 0xa800
	s_nop 0
	global_load_lds_dwordx4 v187, s[12:13]
	s_add_i32 m0, s48, 0xac00
	s_nop 0
	global_load_lds_dwordx4 v186, s[12:13]
	s_cmp_lt_u32 s33, 29
	s_cselect_b32 s43, 0x10000, 0
	s_add_u32 s8, s8, s43
	s_addc_u32 s9, s9, 0
	s_cmp_lt_u32 s33, 29
	s_cselect_b32 s43, 0x2000, 0
	s_add_u32 s10, s10, s43
	s_addc_u32 s11, s11, 0
	s_cmp_lt_u32 s33, 29
	s_cselect_b32 s43, 0x4000, 0
	s_add_u32 s12, s12, s43
	s_addc_u32 s13, s13, 0
	global_load_dwordx4 v[24:27], v255, s[14:15]
	s_cmp_lt_u32 s33, 28
	s_cselect_b32 s43, 0x100000, 0
	s_add_u32 s14, s14, s43
	s_addc_u32 s15, s15, 0
	s_add_i32 s33, s33, 1
	s_waitcnt vmcnt(12)
	s_waitcnt lgkmcnt(0)
	s_barrier
	s_cmp_lt_u32 s33, 30
	s_cbranch_scc1 .Lp3V_loop
	s_waitcnt vmcnt(11)
	ds_write_b16 v216, v20 offset:12288
	ds_write_b16_d16_hi v215, v20 offset:12288
	ds_write_b16 v214, v21 offset:12288
	ds_write_b16_d16_hi v213, v21 offset:12288
	ds_write_b16 v212, v22 offset:12288
	ds_write_b16_d16_hi v211, v22 offset:12288
	ds_write_b16 v210, v23 offset:12288
	ds_write_b16_d16_hi v209, v23 offset:12288
	s_add_i32 m0, s46, 0x14000
	s_nop 0
	global_load_lds_dwordx4 v195, s[8:9]
	s_add_i32 m0, s46, 0x14400
	s_nop 0
	global_load_lds_dwordx4 v194, s[8:9]
	s_add_i32 m0, s47, 0x14000
	s_nop 0
	global_load_lds_dwordx4 v191, s[10:11]
	s_add_i32 m0, s48, 0x14000
	s_nop 0
	global_load_lds_dwordx4 v189, s[12:13]
	s_add_i32 m0, s48, 0x14400
	s_nop 0
	global_load_lds_dwordx4 v188, s[12:13]
	s_add_i32 m0, s46, 0x14800
	s_nop 0
	global_load_lds_dwordx4 v193, s[8:9]
	s_add_i32 m0, s46, 0x14c00
	s_nop 0
	global_load_lds_dwordx4 v192, s[8:9]
	s_add_i32 m0, s47, 0x14400
	s_nop 0
	global_load_lds_dwordx4 v190, s[10:11]
	s_add_i32 m0, s48, 0x14800
	s_nop 0
	global_load_lds_dwordx4 v187, s[12:13]
	s_add_i32 m0, s48, 0x14c00
	s_nop 0
	global_load_lds_dwordx4 v186, s[12:13]
	s_cmp_lt_u32 s33, 29
	s_cselect_b32 s43, 0x10000, 0
	s_add_u32 s8, s8, s43
	s_addc_u32 s9, s9, 0
	s_cmp_lt_u32 s33, 29
	s_cselect_b32 s43, 0x2000, 0
	s_add_u32 s10, s10, s43
	s_addc_u32 s11, s11, 0
	s_cmp_lt_u32 s33, 29
	s_cselect_b32 s43, 0x4000, 0
	s_add_u32 s12, s12, s43
	s_addc_u32 s13, s13, 0
	global_load_dwordx4 v[16:19], v255, s[14:15]
	s_cmp_lt_u32 s33, 28
	s_cselect_b32 s43, 0x100000, 0
	s_add_u32 s14, s14, s43
	s_addc_u32 s15, s15, 0
	s_add_i32 s33, s33, 1
	s_waitcnt vmcnt(12)
	s_waitcnt lgkmcnt(0)
	s_barrier
	s_waitcnt vmcnt(11)
	ds_write_b16 v216, v24 offset:0
	ds_write_b16_d16_hi v215, v24 offset:0
	ds_write_b16 v214, v25 offset:0
	ds_write_b16_d16_hi v213, v25 offset:0
	ds_write_b16 v212, v26 offset:0
	ds_write_b16_d16_hi v211, v26 offset:0
	ds_write_b16 v210, v27 offset:0
	ds_write_b16_d16_hi v209, v27 offset:0
	s_mov_b32 m0, s46
	s_nop 0
	global_load_lds_dwordx4 v195, s[8:9]
	s_add_i32 m0, s46, 0x400
	s_nop 0
	global_load_lds_dwordx4 v194, s[8:9]
	s_mov_b32 m0, s47
	s_nop 0
	global_load_lds_dwordx4 v191, s[10:11]
	s_mov_b32 m0, s48
	s_nop 0
	global_load_lds_dwordx4 v189, s[12:13]
	s_add_i32 m0, s48, 0x400
	s_nop 0
	global_load_lds_dwordx4 v188, s[12:13]
	s_add_i32 m0, s46, 0x800
	s_nop 0
	global_load_lds_dwordx4 v193, s[8:9]
	s_add_i32 m0, s46, 0xc00
	s_nop 0
	global_load_lds_dwordx4 v192, s[8:9]
	s_add_i32 m0, s47, 0x400
	s_nop 0
	global_load_lds_dwordx4 v190, s[10:11]
	s_add_i32 m0, s48, 0x800
	s_nop 0
	global_load_lds_dwordx4 v187, s[12:13]
	s_add_i32 m0, s48, 0xc00
	s_nop 0
	global_load_lds_dwordx4 v186, s[12:13]
	s_cmp_lt_u32 s33, 29
	s_cselect_b32 s43, 0x10000, 0
	s_add_u32 s8, s8, s43
	s_addc_u32 s9, s9, 0
	s_cmp_lt_u32 s33, 29
	s_cselect_b32 s43, 0x2000, 0
	s_add_u32 s10, s10, s43
	s_addc_u32 s11, s11, 0
	s_cmp_lt_u32 s33, 29
	s_cselect_b32 s43, 0x4000, 0
	s_add_u32 s12, s12, s43
	s_addc_u32 s13, s13, 0
	global_load_dwordx4 v[20:23], v255, s[14:15]
	s_cmp_lt_u32 s33, 28
	s_cselect_b32 s43, 0x100000, 0
	s_add_u32 s14, s14, s43
	s_addc_u32 s15, s15, 0
	s_add_i32 s33, s33, 1
	s_waitcnt vmcnt(12)
	s_waitcnt lgkmcnt(0)
	s_barrier
	s_waitcnt vmcnt(0) lgkmcnt(0)
	s_barrier
	s_add_i32 s3, s3, s42
	s_cmpk_lt_i32 s3, 0x100
	s_cbranch_scc1 .Lp3V_item
	s_branch .Lp3_done
